# v9 + unit scheduler: runtime reciprocal (cvt/rcp/readfirstlane) of compile-time-constant divisors replaced by constant magic numbers (57 sites)
# speedup vs baseline: 1.0065x; 1.0003x over previous
; #define PG8_BAR __builtin_amdgcn_s_barrier()
;     __device__ __forceinline__ bool next(int i, Unit& u) const {
;         int nM = this->nM, nN = this->nN, Z2 = this->Z2; asm volatile("" : "+s"(nM), "+s"(nN), "+s"(Z2));
; template <class Epi>
; __device__ __forceinline__ void gemm_phase(PG8_LAS unsigned char* lds, PG8_LAS unsigned char* xl, const Gemm g, const Sched& S, const Epi& E, const int wid) {
;     const int lane = lane_id_opq(), tid = wid * 64 + lane;
;     const int wr = wid >> 2, wc = wid & 3, fr = lane & 15, fq = lane >> 4;
;     const int K = g.K, nt = K / BK;
;     unsigned voffA[2], voffB[2];
; #pragma unroll
;     for (int i = 0; i < 2; ++i) { int R, C; stage_rc(tid * 16 + i * 8192, R, C); const int Rb = Epi::PERM ? ((R & ~31) + perm32(R & 31)) : R;
;         const int Ra = Epi::PERM ? ((R & ~63) + 4 * (R & 15) + ((R >> 4) & 3)) : R;
;         voffA[i] = (unsigned)(Ra * g.lda + C) * 2u; voffB[i] = (unsigned)(Rb * g.ldb + C) * 2u; }
;     const size_t kstep = (size_t)(BK * 2);
;     const size_t hstepA = (size_t)HALF * g.lda * 2, hstepB = (size_t)HALF * g.ldb * 2;
;     const unsigned ldsw = (unsigned)wid * 1024u;
;     const int aoff = lds_byte(wr * 64 + fr, fq * 8), boff = lds_byte(wc * 32 + fr, fq * 8);
;     ...
;     Unit cur, nxt; int ui = 0;
;     if (!S.next(0, cur)) return;
;     Acc acc;
; #pragma unroll
;     for (int a = 0; a < 2; ++a)
; #pragma unroll
;         for (int b = 0; b < 2; ++b)
; #pragma unroll
;             for (int m = 0; m < 4; ++m)
; #pragma unroll
;                 for (int n = 0; n < 2; ++n) acc[a][b][m][n] = (f32x4){0.f, 0.f, 0.f, 0.f};
;     bf16x8 At[4][2], B0[2][2], B1[2][2];
;     float prc[8];
; #pragma unroll
;     for (int k = 0; k < 8; ++k) prc[k] = 1.0f;
;     if constexpr (Epi::PRE) { const float* pb = E.pre_base(cur) + wr * 64 + 4 * fr;
; #pragma unroll
;         for (int k = 0; k < 8; ++k) prc[k] = pb[(k >> 2) * HALF + (k & 3)]; }
;     const char* cA = a_tile(g, cur); const char* cB = b_tile(g, cur);
;     PG8_STAGE(PG8_SB(0, 0), cB, voffB); PG8_STAGE(PG8_SB(0, 1), cB + hstepB, voffB); PG8_STAGE(PG8_SA(0, 0), cA, voffA); PG8_STAGE(PG8_SA(0, 1), cA + hstepA, voffA);
;     if (wr == 1) PG8_BAR;
;     PG8_WAIT_V(2); PG8_BAR;
;     PG8_STAGE(PG8_SB(1, 0), cB + kstep, voffB); PG8_STAGE(PG8_SA(1, 0), cA + kstep, voffA); PG8_STAGE(PG8_SB(1, 1), cB + hstepB + kstep, voffB);
;     PG8_WAIT_V(6); PG8_BAR;
.LBB0_211:
	v_readlane_b32 s8, v253, 0
	v_readlane_b32 s9, v253, 1
	s_mov_b32 s0, s36
	s_waitcnt lgkmcnt(0)
	s_barrier
	s_load_dwordx4 s[44:47], s[8:9], 0xd0
	v_readlane_b32 s4, v254, 16
	v_readlane_b32 s1, v254, 13
	v_readlane_b32 s5, v254, 17
	s_add_i32 s1, s0, s1
	s_mov_b32 s8, 20
	v_cndmask_b32_e64 v0, 0, 1, s[4:5]
	s_mov_b32 s10, 1
	s_mov_b32 s9, 16
	s_cmpk_gt_i32 s1, 0x13f
	v_cmp_ne_u32_e64 s[38:39], 1, v0
	v_mbcnt_lo_u32_b32 v8, -1, 0
	v_mbcnt_hi_u32_b32 v8, -1, v8
	s_cbranch_scc1 .LBB0_227
	v_lshlrev_b32_e32 v10, 4, v8
	v_add_u32_e32 v0, s29, v10
	v_add_u32_e32 v1, 0x2000, v0
	v_ashrrev_i32_e32 v2, 31, v1
	v_lshrrev_b32_e32 v2, 22, v2
	v_add_u32_e32 v2, v1, v2
	v_ashrrev_i32_e32 v9, 10, v2
	v_mul_i32_i24_e32 v2, 0x400, v9
	v_sub_u32_e32 v1, v1, v2
	v_lshrrev_b32_e32 v2, 4, v1
	v_bitop3_b32 v1, v2, v1, 32 bitop3:0x6c
	v_ashrrev_i32_e32 v2, 31, v1
	v_lshrrev_b32_e32 v2, 26, v2
	v_add_u32_e32 v2, v1, v2
	v_ashrrev_i32_e32 v3, 6, v2
	v_lshlrev_b32_e32 v4, 3, v9
	v_and_b32_e32 v2, 0xffc0, v2
	v_and_b32_e32 v4, -16, v4
	v_sub_u32_e32 v1, v1, v2
	v_add_u32_e32 v4, v3, v4
	v_lshrrev_b16_e32 v2, 7, v1
	v_and_b32_e32 v3, 3, v3
	s_mov_b32 s4, 0xfffe0
	v_lshrrev_b32_e32 v5, 2, v4
	v_lshlrev_b32_e32 v6, 1, v4
	v_and_b32_e32 v2, 1, v2
	v_and_or_b32 v3, v4, s4, v3
	v_and_b32_e32 v5, 4, v5
	v_and_b32_e32 v6, 24, v6
	v_add_u16_e32 v1, v1, v2
	v_or3_b32 v3, v3, v5, v6
	v_lshlrev_b32_e32 v5, 5, v9
	v_ashrrev_i16_sdwa v1, v244, sext(v1) dst_sel:DWORD dst_unused:UNUSED_PAD src0_sel:DWORD src1_sel:BYTE_0
	v_lshlrev_b32_e32 v2, 2, v4
	v_and_b32_e32 v5, 32, v5
	v_bfe_i32 v11, v1, 0, 16
	v_and_b32_e32 v12, 0xfffc0, v4
	v_and_b32_e32 v13, 60, v2
	v_bfe_u32 v14, v4, 4, 2
	v_add_lshl_u32 v1, v5, v11, 1
	v_or3_b32 v2, v12, v13, v14
	v_lshl_add_u32 v128, v3, 12, v1
	v_lshl_add_u32 v130, v2, 12, v1
	v_ashrrev_i32_e32 v1, 31, v0
	v_lshrrev_b32_e32 v1, 22, v1
	s_waitcnt lgkmcnt(0)
	s_add_u32 s60, s46, 0x14c00000
	v_add_u32_e32 v1, v0, v1
	s_addc_u32 s61, s47, 0
	v_ashrrev_i32_e32 v15, 10, v1
	s_add_u32 s62, s46, 0x5000000
	v_mul_i32_i24_e32 v1, 0x400, v15
	s_addc_u32 s66, s47, 0
	v_sub_u32_e32 v0, v0, v1
	s_ashr_i32 s67, s1, 31
	v_lshrrev_b32_e32 v1, 4, v0
	s_lshr_b32 s10, s67, 29
	v_bitop3_b32 v0, v1, v0, 32 bitop3:0x6c
	s_add_i32 s10, s1, s10
	v_ashrrev_i32_e32 v1, 31, v0
	s_ashr_i32 s11, s10, 3
	s_and_b32 s10, s10, -8
	v_lshrrev_b32_e32 v1, 26, v1
	s_sub_i32 s10, s1, s10
	v_add_u32_e32 v1, v0, v1
	s_cmp_lt_i32 s10, 0
	s_mul_i32 s13, s8, s9
	v_ashrrev_i32_e32 v2, 6, v1
	v_and_b32_e32 v1, 0xc0, v1
	s_cselect_b32 s12, 41, 40
	s_abs_i32 s13, s13
	v_sub_u32_e32 v0, v0, v1
	s_mul_i32 s10, s10, s12
	s_sub_i32 s12, 0, s13
	s_add_i32 s10, s10, s11
	s_ashr_i32 s11, s10, 31
	s_abs_i32 s10, s10
	v_lshlrev_b32_e32 v3, 3, v15
	v_and_b32_e32 v3, -16, v3
	v_add_u32_e32 v3, v2, v3
	v_and_b32_e32 v2, 3, v2
	s_mov_b32 s20, 0xcccccc
	s_mul_i32 s12, s12, s20
	s_mul_hi_u32 s12, s20, s12
	s_add_i32 s20, s20, s12
	s_mul_hi_u32 s12, s10, s20
	s_mul_i32 s12, s12, s13
	s_sub_i32 s10, s10, s12
	s_sub_i32 s12, s10, s13
	s_cmp_ge_u32 s10, s13
	s_cselect_b32 s10, s12, s10
	s_sub_i32 s12, s10, s13
	s_cmp_ge_u32 s10, s13
	s_cselect_b32 s10, s12, s10
	s_lshl_b32 s9, s9, 2
	s_abs_i32 s12, s9
	s_sub_i32 s20, 0, s12
	s_xor_b32 s10, s10, s11
	s_sub_i32 s10, s10, s11
	s_abs_i32 s13, s10
	s_xor_b32 s11, s10, s9
	s_ashr_i32 s11, s11, 31
	v_lshrrev_b32_e32 v4, 2, v3
	v_lshlrev_b32_e32 v5, 1, v3
	v_and_or_b32 v2, v3, s4, v2
	s_mov_b32 s21, 0x4000000
	s_mul_i32 s20, s20, s21
	s_mul_hi_u32 s20, s21, s20
	s_add_i32 s21, s21, s20
	s_mul_hi_u32 s20, s13, s21
	s_mul_i32 s21, s20, s12
	s_sub_i32 s13, s13, s21
	s_add_i32 s21, s20, 1
	s_sub_i32 s30, s13, s12
	s_cmp_ge_u32 s13, s12
	s_cselect_b32 s20, s21, s20
	s_cselect_b32 s13, s30, s13
	s_add_i32 s21, s20, 1
	s_cmp_ge_u32 s13, s12
	s_cselect_b32 s12, s21, s20
	s_xor_b32 s12, s12, s11
	s_sub_i32 s11, s12, s11
	s_lshl_b32 s12, s11, 2
	v_and_b32_e32 v4, 4, v4
	v_and_b32_e32 v5, 24, v5
	s_sub_i32 s8, s8, s12
	v_or3_b32 v2, v2, v4, v5
	v_lshlrev_b32_e32 v4, 5, v15
	v_ashrrev_i16_sdwa v0, v244, sext(v0) dst_sel:DWORD dst_unused:UNUSED_PAD src0_sel:DWORD src1_sel:BYTE_0
	s_min_i32 s8, s8, 4
	v_and_b32_e32 v4, 32, v4
	v_bfe_i32 v16, v0, 0, 16
	s_abs_i32 s13, s8
	v_add_lshl_u32 v0, v4, v16, 1
	v_cvt_f32_u32_e32 v1, s13
	v_lshl_add_u32 v132, v2, 12, v0
	v_lshlrev_b32_e32 v2, 2, v3
	v_and_b32_e32 v17, 0xfffc0, v3
	v_and_b32_e32 v18, 60, v2
	v_bfe_u32 v19, v3, 4, 2
	v_or3_b32 v2, v17, v18, v19
	v_lshl_add_u32 v134, v2, 12, v0
	v_rcp_iflag_f32_e32 v0, v1
	s_sub_i32 s20, 0, s13
	s_mul_i32 s11, s11, s9
	s_sub_i32 s9, s10, s11
	v_mul_f32_e32 v0, 0x4f7ffffe, v0
	v_cvt_u32_f32_e32 v0, v0
	s_abs_i32 s11, s9
	s_xor_b32 s10, s9, s8
	s_ashr_i32 s10, s10, 31
	v_readfirstlane_b32 s21, v0
	s_mul_i32 s20, s20, s21
	s_mul_hi_u32 s20, s21, s20
	s_add_i32 s21, s21, s20
	s_mul_hi_u32 s20, s11, s21
	s_mul_i32 s21, s20, s13
	s_sub_i32 s11, s11, s21
	s_add_i32 s21, s20, 1
	s_sub_i32 s30, s11, s13
	s_cmp_ge_u32 s11, s13
	s_cselect_b32 s20, s21, s20
	s_cselect_b32 s11, s30, s11
	s_add_i32 s21, s20, 1
	s_cmp_ge_u32 s11, s13
	s_cselect_b32 s11, s21, s20
	s_xor_b32 s11, s11, s10
	s_sub_i32 s36, s11, s10
	s_mul_i32 s8, s36, s8
	s_sub_i32 s8, s9, s8
	s_ashr_i32 s37, s36, 31
	s_add_i32 s42, s12, s8
	s_lshl_b64 s[8:9], s[36:37], 20
	s_add_u32 s52, s62, s8
	s_addc_u32 s53, s66, s9
	s_add_i32 s37, s29, 0
	s_add_i32 m0, s37, 0x10000
	s_ashr_i32 s43, s42, 31
	global_load_lds_dwordx4 v132, s[52:53]
	s_add_i32 m0, s37, 0x12000
	s_add_u32 s8, s52, 0x80000
	global_load_lds_dwordx4 v128, s[52:53]
	s_addc_u32 s9, s53, 0
	s_add_i32 m0, s37, 0x14000
	v_mov_b32_e32 v133, v193
	global_load_lds_dwordx4 v132, s[8:9]
	s_add_i32 m0, s37, 0x16000
	v_mov_b32_e32 v129, v193
	global_load_lds_dwordx4 v128, s[8:9]
	s_lshl_b64 s[8:9], s[42:43], 20
	s_add_u32 s50, s60, s8
	s_addc_u32 s51, s61, s9
	s_add_i32 s68, s37, 0x2000
	s_mov_b32 m0, s37
	s_add_u32 s8, s50, 0x80000
	global_load_lds_dwordx4 v134, s[50:51]
	s_mov_b32 m0, s68
	s_addc_u32 s9, s51, 0
	s_add_i32 s69, s37, 0x4000
	global_load_lds_dwordx4 v130, s[50:51]
	s_mov_b32 m0, s69
	s_add_i32 s70, s37, 0x6000
	global_load_lds_dwordx4 v134, s[8:9]
	s_mov_b32 m0, s70
	v_mov_b32_e32 v135, v193
	global_load_lds_dwordx4 v130, s[8:9]
	v_mov_b32_e32 v131, v193
	v_lshl_add_u64 v[6:7], s[52:53], 0, v[132:133]
	v_lshl_add_u64 v[4:5], s[52:53], 0, v[128:129]
	v_lshl_add_u64 v[2:3], s[50:51], 0, v[134:135]
	s_and_b64 vcc, exec, s[38:39]
	v_lshl_add_u64 v[0:1], s[50:51], 0, v[130:131]
	s_cbranch_vccnz .LBB0_214
	s_barrier

;     __device__ __forceinline__ bool next(int i, Unit& u) const {
;         int nM = this->nM, nN = this->nN, Z2 = this->Z2; asm volatile("" : "+s"(nM), "+s"(nN), "+s"(Z2));
;         const long L = (long)i * G + c; if (L >= nwg) return false;
;         int wgid = (int)L; { const int q = nwg / NXCD, r = nwg % NXCD, xcd = wgid % NXCD, off = wgid / NXCD; wgid = (xcd < r ? xcd * (q + 1) : r * (q + 1) + (xcd - r) * q) + off; }
;         if (rev) wgid = nwg - 1 - wgid;
;         const int per = nM * nN, z = wgid / per, rem = wgid - z * per;
;         const int nig = WGM * nN, gid = rem / nig, fm = gid * WGM, gsz = (nM - fm) < WGM ? (nM - fm) : WGM, ri = rem - gid * nig;
;         u.pm = fm + (ri % gsz); u.pn = ri / gsz; u.z1 = z / Z2; u.z2 = z - u.z1 * Z2; return true;
.LBB0_217:
	s_mov_b32 s8, 20
	s_mov_b32 s10, 1
	s_mov_b32 s9, 16
	s_add_i32 s89, s89, 1
	s_mul_i32 s10, s89, s88
	s_mul_hi_u32 s11, s89, s0
	s_add_i32 s11, s11, s10
	s_mul_i32 s10, s89, s0
	s_add_u32 s10, s10, s1
	s_addc_u32 s11, s11, s67
	v_mov_b64_e32 v[0:1], 0x140
	v_cmp_lt_i64_e64 s[40:41], s[10:11], v[0:1]
	v_mov_b64_e32 v[0:1], 0x13f
	v_cmp_gt_i64_e32 vcc, s[10:11], v[0:1]
	s_cbranch_vccnz .LBB0_219
	s_ashr_i32 s11, s10, 31
	s_lshr_b32 s11, s11, 29
	s_add_i32 s11, s10, s11
	s_ashr_i32 s12, s11, 3
	s_and_b32 s11, s11, -8
	s_sub_i32 s10, s10, s11
	s_cmp_lt_i32 s10, 0
	s_mul_i32 s13, s8, s9
	s_cselect_b32 s11, 41, 40
	s_abs_i32 s13, s13
	s_mul_i32 s10, s10, s11
	s_sub_i32 s11, 0, s13
	s_add_i32 s10, s10, s12
	s_ashr_i32 s12, s10, 31
	s_abs_i32 s10, s10
	s_mov_b32 s20, 0xcccccc
	s_mul_i32 s11, s11, s20
	s_mul_hi_u32 s11, s20, s11
	s_add_i32 s20, s20, s11
	s_mul_hi_u32 s11, s10, s20
	s_mul_i32 s11, s11, s13
	s_sub_i32 s10, s10, s11
	s_sub_i32 s11, s10, s13
	s_cmp_ge_u32 s10, s13
	s_cselect_b32 s10, s11, s10
	s_sub_i32 s11, s10, s13
	s_cmp_ge_u32 s10, s13
	s_cselect_b32 s10, s11, s10
	s_lshl_b32 s9, s9, 2
	s_abs_i32 s11, s9
	s_xor_b32 s10, s10, s12
	s_sub_i32 s10, s10, s12
	s_sub_i32 s12, 0, s11
	s_abs_i32 s20, s10
	s_xor_b32 s13, s10, s9
	s_ashr_i32 s13, s13, 31
	s_mov_b32 s21, 0x4000000
	s_mul_i32 s12, s12, s21
	s_mul_hi_u32 s12, s21, s12
	s_add_i32 s21, s21, s12
	s_mul_hi_u32 s12, s20, s21
	s_mul_i32 s21, s12, s11
	s_sub_i32 s20, s20, s21
	s_add_i32 s30, s12, 1
	s_sub_i32 s21, s20, s11
	s_cmp_ge_u32 s20, s11
	s_cselect_b32 s12, s30, s12
	s_cselect_b32 s20, s21, s20
	s_add_i32 s21, s12, 1
	s_cmp_ge_u32 s20, s11
	s_cselect_b32 s11, s21, s12
	s_xor_b32 s11, s11, s13
	s_sub_i32 s11, s11, s13
	s_lshl_b32 s13, s11, 2
	s_sub_i32 s8, s8, s13
	s_min_i32 s8, s8, 4
	s_abs_i32 s12, s8
	v_cvt_f32_u32_e32 v0, s12
	s_sub_i32 s20, 0, s12
	s_mul_i32 s11, s11, s9
	s_sub_i32 s9, s10, s11
	v_rcp_iflag_f32_e32 v0, v0
	s_abs_i32 s10, s9
	s_xor_b32 s11, s9, s8
	s_ashr_i32 s11, s11, 31
	v_mul_f32_e32 v0, 0x4f7ffffe, v0
	v_cvt_u32_f32_e32 v0, v0
	s_nop 0
	v_readfirstlane_b32 s21, v0
	s_mul_i32 s20, s20, s21
	s_mul_hi_u32 s20, s21, s20
	s_add_i32 s21, s21, s20
	s_mul_hi_u32 s20, s10, s21
	s_mul_i32 s21, s20, s12
	s_sub_i32 s10, s10, s21
	s_add_i32 s30, s20, 1
	s_sub_i32 s21, s10, s12
	s_cmp_ge_u32 s10, s12
	s_cselect_b32 s20, s30, s20
	s_cselect_b32 s10, s21, s10
	s_add_i32 s21, s20, 1
	s_cmp_ge_u32 s10, s12
	s_cselect_b32 s10, s21, s20
	s_xor_b32 s10, s10, s11
	s_sub_i32 s12, s10, s11
	s_mul_i32 s8, s12, s8
	s_sub_i32 s8, s9, s8
	s_add_i32 s20, s13, s8

;     __device__ __forceinline__ bool next(int i, Unit& u) const {
;         int nM = this->nM, nN = this->nN, Z2 = this->Z2; asm volatile("" : "+s"(nM), "+s"(nN), "+s"(Z2));
;         const long L = (long)i * G + c; if (L >= nwg) return false;
;         int wgid = (int)L; { const int q = nwg / NXCD, r = nwg % NXCD, xcd = wgid % NXCD, off = wgid / NXCD; wgid = (xcd < r ? xcd * (q + 1) : r * (q + 1) + (xcd - r) * q) + off; }
;         if (rev) wgid = nwg - 1 - wgid;
;         const int per = nM * nN, z = wgid / per, rem = wgid - z * per;
;         const int nig = WGM * nN, gid = rem / nig, fm = gid * WGM, gsz = (nM - fm) < WGM ? (nM - fm) : WGM, ri = rem - gid * nig;
;         u.pm = fm + (ri % gsz); u.pn = ri / gsz; u.z1 = z / Z2; u.z2 = z - u.z1 * Z2; return true;
.LBB0_227:
	v_readlane_b32 s4, v254, 20
	v_readlane_b32 s5, v254, 21
	s_mov_b32 s9, 1
	s_movk_i32 s1, 0xa0
	v_cndmask_b32_e64 v0, 0, 1, s[4:5]
	s_mov_b32 s8, 28
	v_cmp_ne_u32_e64 s[40:41], 1, v0
	s_andn2_b64 vcc, exec, s[4:5]
	v_mbcnt_lo_u32_b32 v8, -1, 0
	v_mbcnt_hi_u32_b32 v8, -1, v8
	s_cbranch_vccnz .LBB0_229
	s_mul_i32 s9, s1, s8
	s_abs_i32 s9, s9
	s_sub_i32 s10, 0, s9
	v_readlane_b32 s4, v254, 49
	s_nop 0
	s_mov_b32 s11, 0xea0ea
	s_mul_i32 s10, s10, s11
	s_mul_hi_u32 s10, s11, s10
	s_add_i32 s11, s11, s10
	s_mul_hi_u32 s10, s4, s11
	s_mul_i32 s10, s10, s9
	s_sub_i32 s10, s4, s10
	s_sub_i32 s11, s10, s9
	s_cmp_ge_u32 s10, s9
	s_cselect_b32 s10, s11, s10
	s_sub_i32 s11, s10, s9
	s_cmp_ge_u32 s10, s9
	s_cselect_b32 s9, s11, s10
	s_lshl_b32 s8, s8, 2
	s_abs_i32 s10, s8
	v_readlane_b32 s4, v254, 48
	s_sub_i32 s11, 0, s10
	s_xor_b32 s9, s9, s4
	s_sub_i32 s9, s9, s4
	s_abs_i32 s13, s9
	s_xor_b32 s12, s9, s8
	s_ashr_i32 s12, s12, 31
	s_mov_b32 s20, 0x2492492
	s_mul_i32 s11, s11, s20
	s_mul_hi_u32 s11, s20, s11
	s_add_i32 s20, s20, s11
	s_mul_hi_u32 s11, s13, s20
	s_mul_i32 s20, s11, s10
	s_sub_i32 s13, s13, s20
	s_add_i32 s21, s11, 1
	s_sub_i32 s20, s13, s10
	s_cmp_ge_u32 s13, s10
	s_cselect_b32 s11, s21, s11
	s_cselect_b32 s13, s20, s13
	s_add_i32 s20, s11, 1
	s_cmp_ge_u32 s13, s10
	s_cselect_b32 s10, s20, s11
	s_xor_b32 s10, s10, s12
	s_sub_i32 s10, s10, s12
	s_lshl_b32 s11, s10, 2
	s_sub_i32 s1, s1, s11
	s_min_i32 s1, s1, 4
	s_abs_i32 s12, s1
	v_cvt_f32_u32_e32 v0, s12
	s_sub_i32 s13, 0, s12
	s_mul_i32 s10, s10, s8
	s_sub_i32 s8, s9, s10
	v_rcp_iflag_f32_e32 v0, v0
	s_abs_i32 s9, s8
	s_xor_b32 s10, s8, s1
	s_ashr_i32 s10, s10, 31
	v_mul_f32_e32 v0, 0x4f7ffffe, v0
	v_cvt_u32_f32_e32 v0, v0
	s_nop 0
	v_readfirstlane_b32 s20, v0
	s_mul_i32 s13, s13, s20
	s_mul_hi_u32 s13, s20, s13
	s_add_i32 s20, s20, s13
	s_mul_hi_u32 s13, s9, s20
	s_mul_i32 s20, s13, s12
	s_sub_i32 s9, s9, s20
	s_add_i32 s21, s13, 1
	s_sub_i32 s20, s9, s12
	s_cmp_ge_u32 s9, s12
	s_cselect_b32 s13, s21, s13
	s_cselect_b32 s9, s20, s9
	s_add_i32 s20, s13, 1
	s_cmp_ge_u32 s9, s12
	s_cselect_b32 s9, s20, s13
	s_xor_b32 s9, s9, s10
	s_sub_i32 s12, s9, s10
	s_mul_i32 s1, s12, s1
	s_sub_i32 s1, s8, s1
	s_add_i32 s48, s11, s1

;     __device__ __forceinline__ bool next(int i, Unit& u) const {
;         int nM = this->nM, nN = this->nN, Z2 = this->Z2; asm volatile("" : "+s"(nM), "+s"(nN), "+s"(Z2));
;         const long L = (long)i * G + c; if (L >= nwg) return false;
;         int wgid = (int)L; { const int q = nwg / NXCD, r = nwg % NXCD, xcd = wgid % NXCD, off = wgid / NXCD; wgid = (xcd < r ? xcd * (q + 1) : r * (q + 1) + (xcd - r) * q) + off; }
;         if (rev) wgid = nwg - 1 - wgid;
;         const int per = nM * nN, z = wgid / per, rem = wgid - z * per;
;         const int nig = WGM * nN, gid = rem / nig, fm = gid * WGM, gsz = (nM - fm) < WGM ? (nM - fm) : WGM, ri = rem - gid * nig;
;         u.pm = fm + (ri % gsz); u.pn = ri / gsz; u.z1 = z / Z2; u.z2 = z - u.z1 * Z2; return true;
.LBB0_235:
	s_mov_b32 s10, 1
	s_movk_i32 s8, 0xa0
	s_mov_b32 s9, 28
	s_add_i32 s96, s96, 1
	s_mul_i32 s10, s96, s95
	s_mul_hi_u32 s11, s96, s0
	s_add_i32 s11, s11, s10
	s_mul_i32 s10, s96, s0
	s_add_u32 s10, s10, s2
	s_addc_u32 s11, s11, s33
	v_mov_b64_e32 v[0:1], 0x1180
	v_cmp_lt_i64_e64 s[40:41], s[10:11], v[0:1]
	v_mov_b64_e32 v[0:1], 0x117f
	v_cmp_gt_i64_e64 s[42:43], s[10:11], v[0:1]
	s_and_b64 vcc, exec, s[42:43]
	s_cbranch_vccnz .LBB0_237
	s_ashr_i32 s11, s10, 31
	s_lshr_b32 s11, s11, 29
	s_add_i32 s11, s10, s11
	s_and_b32 s13, s11, -8
	s_sub_i32 s10, s10, s13
	s_ashr_i32 s11, s11, 3
	s_cmp_lt_i32 s10, 0
	s_mul_i32 s36, s8, s9
	s_cselect_b32 s13, s4, 0xfffffdd0
	s_abs_i32 s36, s36
	s_mul_i32 s10, s10, s13
	s_sub_i32 s13, 0, s36
	s_sub_i32 s10, s10, s11
	s_addk_i32 s10, 0x117f
	s_ashr_i32 s11, s10, 31
	s_abs_i32 s10, s10
	s_mov_b32 s37, 0xea0ea
	s_mul_i32 s13, s13, s37
	s_mul_hi_u32 s13, s37, s13
	s_add_i32 s37, s37, s13
	s_mul_hi_u32 s13, s10, s37
	s_mul_i32 s13, s13, s36
	s_sub_i32 s10, s10, s13
	s_sub_i32 s13, s10, s36
	s_cmp_ge_u32 s10, s36
	s_cselect_b32 s10, s13, s10
	s_sub_i32 s13, s10, s36
	s_cmp_ge_u32 s10, s36
	s_cselect_b32 s10, s13, s10
	s_lshl_b32 s9, s9, 2
	s_abs_i32 s13, s9
	s_xor_b32 s10, s10, s11
	s_sub_i32 s10, s10, s11
	s_sub_i32 s11, 0, s13
	s_abs_i32 s37, s10
	s_xor_b32 s36, s10, s9
	s_ashr_i32 s36, s36, 31
	s_mov_b32 s44, 0x2492492
	s_mul_i32 s11, s11, s44
	s_mul_hi_u32 s11, s44, s11
	s_add_i32 s44, s44, s11
	s_mul_hi_u32 s11, s37, s44
	s_mul_i32 s44, s11, s13
	s_sub_i32 s37, s37, s44
	s_add_i32 s45, s11, 1
	s_sub_i32 s44, s37, s13
	s_cmp_ge_u32 s37, s13
	s_cselect_b32 s11, s45, s11
	s_cselect_b32 s37, s44, s37
	s_add_i32 s44, s11, 1
	s_cmp_ge_u32 s37, s13
	s_cselect_b32 s11, s44, s11
	s_xor_b32 s11, s11, s36
	s_sub_i32 s11, s11, s36
	s_lshl_b32 s13, s11, 2
	s_sub_i32 s8, s8, s13
	s_min_i32 s8, s8, 4
	s_abs_i32 s36, s8
	v_cvt_f32_u32_e32 v0, s36
	s_sub_i32 s37, 0, s36
	s_mul_i32 s11, s11, s9
	s_sub_i32 s9, s10, s11
	v_rcp_iflag_f32_e32 v0, v0
	s_abs_i32 s10, s9
	s_xor_b32 s11, s9, s8
	s_ashr_i32 s11, s11, 31
	v_mul_f32_e32 v0, 0x4f7ffffe, v0
	v_cvt_u32_f32_e32 v0, v0
	s_nop 0
	v_readfirstlane_b32 s44, v0
	s_mul_i32 s37, s37, s44
	s_mul_hi_u32 s37, s44, s37
	s_add_i32 s44, s44, s37
	s_mul_hi_u32 s37, s10, s44
	s_mul_i32 s44, s37, s36
	s_sub_i32 s10, s10, s44
	s_add_i32 s45, s37, 1
	s_sub_i32 s44, s10, s36
	s_cmp_ge_u32 s10, s36
	s_cselect_b32 s37, s45, s37
	s_cselect_b32 s10, s44, s10
	s_add_i32 s44, s37, 1
	s_cmp_ge_u32 s10, s36
	s_cselect_b32 s10, s44, s37
	s_xor_b32 s10, s10, s11
	s_sub_i32 s56, s10, s11
	s_mul_i32 s8, s56, s8
	s_sub_i32 s8, s9, s8
	s_add_i32 s58, s13, s8

; #define PG8_LAS __attribute__((address_space(3)))
; __device__ __forceinline__ int lane_id_opq() { int l; asm volatile("v_mbcnt_lo_u32_b32 %0, -1, 0\n\tv_mbcnt_hi_u32_b32 %0, -1, %0" : "=v"(l)); return l; }
; template <class Epi>
; __device__ __forceinline__ void gemm_phase(PG8_LAS unsigned char* lds, PG8_LAS unsigned char* xl, const Gemm g, const Sched& S, const Epi& E, const int wid) {
;     const int lane = lane_id_opq(), tid = wid * 64 + lane;
;     const int wr = wid >> 2, wc = wid & 3, fr = lane & 15, fq = lane >> 4;
;     const int K = g.K, nt = K / BK;
;     unsigned voffA[2], voffB[2];
; #pragma unroll
;     for (int i = 0; i < 2; ++i) { int R, C; stage_rc(tid * 16 + i * 8192, R, C); const int Rb = Epi::PERM ? ((R & ~31) + perm32(R & 31)) : R;
;         const int Ra = Epi::PERM ? ((R & ~63) + 4 * (R & 15) + ((R >> 4) & 3)) : R;
;         voffA[i] = (unsigned)(Ra * g.lda + C) * 2u; voffB[i] = (unsigned)(Rb * g.ldb + C) * 2u; }
;     const size_t kstep = (size_t)(BK * 2);
;     const size_t hstepA = (size_t)HALF * g.lda * 2, hstepB = (size_t)HALF * g.ldb * 2;
;     const unsigned ldsw = (unsigned)wid * 1024u;
;     const int aoff = lds_byte(wr * 64 + fr, fq * 8), boff = lds_byte(wc * 32 + fr, fq * 8);
;     ...
;     Unit cur, nxt; int ui = 0;
;     if (!S.next(0, cur)) return;
.LBB0_395:
	v_readlane_b32 s0, v254, 27
	v_readlane_b32 s1, v254, 28
	s_mov_b32 s10, 8
	s_mov_b32 s9, 1
	v_cndmask_b32_e64 v0, 0, 1, s[0:1]
	v_cmp_ne_u32_e64 s[4:5], 1, v0
	s_mov_b32 s8, 4
	s_andn2_b64 vcc, exec, s[0:1]
	v_writelane_b32 v252, s4, 54
	v_mbcnt_lo_u32_b32 v8, -1, 0
	v_mbcnt_hi_u32_b32 v8, -1, v8
	s_nop 1
	v_writelane_b32 v252, s5, 55
	s_cbranch_vccnz .LBB0_415
; #define PG8_BAR __builtin_amdgcn_s_barrier()
;     __device__ __forceinline__ bool next(int i, Unit& u) const {
;         int nM = this->nM, nN = this->nN, Z2 = this->Z2; asm volatile("" : "+s"(nM), "+s"(nN), "+s"(Z2));
; template <class Epi>
; __device__ __forceinline__ void gemm_phase(PG8_LAS unsigned char* lds, PG8_LAS unsigned char* xl, const Gemm g, const Sched& S, const Epi& E, const int wid) {
;     const int lane = lane_id_opq(), tid = wid * 64 + lane;
;     const int wr = wid >> 2, wc = wid & 3, fr = lane & 15, fq = lane >> 4;
;     const int K = g.K, nt = K / BK;
;     unsigned voffA[2], voffB[2];
; #pragma unroll
;     for (int i = 0; i < 2; ++i) { int R, C; stage_rc(tid * 16 + i * 8192, R, C); const int Rb = Epi::PERM ? ((R & ~31) + perm32(R & 31)) : R;
;         const int Ra = Epi::PERM ? ((R & ~63) + 4 * (R & 15) + ((R >> 4) & 3)) : R;
;         voffA[i] = (unsigned)(Ra * g.lda + C) * 2u; voffB[i] = (unsigned)(Rb * g.ldb + C) * 2u; }
;     const size_t kstep = (size_t)(BK * 2);
;     const size_t hstepA = (size_t)HALF * g.lda * 2, hstepB = (size_t)HALF * g.ldb * 2;
;     const unsigned ldsw = (unsigned)wid * 1024u;
;     const int aoff = lds_byte(wr * 64 + fr, fq * 8), boff = lds_byte(wc * 32 + fr, fq * 8);
;     ...
;     Unit cur, nxt; int ui = 0;
;     if (!S.next(0, cur)) return;
;     Acc acc;
; #pragma unroll
;     for (int a = 0; a < 2; ++a)
; #pragma unroll
;         for (int b = 0; b < 2; ++b)
; #pragma unroll
;             for (int m = 0; m < 4; ++m)
; #pragma unroll
;                 for (int n = 0; n < 2; ++n) acc[a][b][m][n] = (f32x4){0.f, 0.f, 0.f, 0.f};
;     bf16x8 At[4][2], B0[2][2], B1[2][2];
;     float prc[8];
; #pragma unroll
;     for (int k = 0; k < 8; ++k) prc[k] = 1.0f;
;     if constexpr (Epi::PRE) { const float* pb = E.pre_base(cur) + wr * 64 + 4 * fr;
; #pragma unroll
;         for (int k = 0; k < 8; ++k) prc[k] = pb[(k >> 2) * HALF + (k & 3)]; }
;     const char* cA = a_tile(g, cur); const char* cB = b_tile(g, cur);
;     PG8_STAGE(PG8_SB(0, 0), cB, voffB); PG8_STAGE(PG8_SB(0, 1), cB + hstepB, voffB); PG8_STAGE(PG8_SA(0, 0), cA, voffA); PG8_STAGE(PG8_SA(0, 1), cA + hstepA, voffA);
;     if (wr == 1) PG8_BAR;
;     PG8_WAIT_V(2); PG8_BAR;
;     PG8_STAGE(PG8_SB(1, 0), cB + kstep, voffB); PG8_STAGE(PG8_SA(1, 0), cA + kstep, voffA); PG8_STAGE(PG8_SB(1, 1), cB + hstepB + kstep, voffB);
;     PG8_WAIT_V(6); PG8_BAR;
	v_lshlrev_b32_e32 v10, 4, v8
	v_add_u32_e32 v0, s29, v10
	v_add_u32_e32 v1, 0x2000, v0
	v_ashrrev_i32_e32 v2, 31, v1
	v_lshrrev_b32_e32 v2, 22, v2
	v_add_u32_e32 v2, v1, v2
	v_ashrrev_i32_e32 v9, 10, v2
	v_mul_i32_i24_e32 v2, 0x400, v9
	v_sub_u32_e32 v1, v1, v2
	v_lshrrev_b32_e32 v2, 4, v1
	v_bitop3_b32 v1, v2, v1, 32 bitop3:0x6c
	v_ashrrev_i32_e32 v2, 31, v1
	v_lshrrev_b32_e32 v2, 26, v2
	v_add_u32_e32 v2, v1, v2
	v_ashrrev_i32_e32 v3, 6, v2
	v_lshlrev_b32_e32 v4, 3, v9
	v_and_b32_e32 v2, 0xffc0, v2
	v_and_b32_e32 v4, -16, v4
	v_sub_u32_e32 v1, v1, v2
	v_add_u32_e32 v4, v3, v4
	v_lshrrev_b16_e32 v2, 7, v1
	v_and_b32_e32 v3, 3, v3
	s_mov_b32 s4, 0xfffe0
	v_lshrrev_b32_e32 v5, 2, v4
	v_lshlrev_b32_e32 v6, 1, v4
	v_and_b32_e32 v2, 1, v2
	v_and_or_b32 v3, v4, s4, v3
	v_and_b32_e32 v5, 4, v5
	v_and_b32_e32 v6, 24, v6
	v_add_u16_e32 v1, v1, v2
	v_or3_b32 v3, v3, v5, v6
	v_lshlrev_b32_e32 v5, 5, v9
	v_ashrrev_i16_sdwa v1, v244, sext(v1) dst_sel:DWORD dst_unused:UNUSED_PAD src0_sel:DWORD src1_sel:BYTE_0
	v_lshlrev_b32_e32 v2, 2, v4
	v_and_b32_e32 v5, 32, v5
	v_bfe_i32 v11, v1, 0, 16
	v_and_b32_e32 v12, 0x7ffc0, v4
	v_and_b32_e32 v13, 60, v2
	v_bfe_u32 v14, v4, 4, 2
	v_add_lshl_u32 v1, v5, v11, 1
	v_or3_b32 v2, v12, v13, v14
	v_lshl_add_u32 v128, v3, 12, v1
	v_lshl_add_u32 v130, v2, 13, v1
	v_ashrrev_i32_e32 v1, 31, v0
	v_lshrrev_b32_e32 v1, 22, v1
	v_add_u32_e32 v1, v0, v1
	v_ashrrev_i32_e32 v15, 10, v1
	v_mul_i32_i24_e32 v1, 0x400, v15
	v_sub_u32_e32 v0, v0, v1
	v_lshrrev_b32_e32 v1, 4, v0
	v_bitop3_b32 v0, v1, v0, 32 bitop3:0x6c
	s_waitcnt lgkmcnt(0)
	s_add_u32 s0, s50, 0x4800000
	v_ashrrev_i32_e32 v1, 31, v0
	s_addc_u32 s1, s51, 0
	v_lshrrev_b32_e32 v1, 26, v1
	s_add_u32 s62, s50, 0x16000000
	v_add_u32_e32 v1, v0, v1
	s_mul_i32 s11, s9, s10
	s_addc_u32 s66, s51, 0
	v_ashrrev_i32_e32 v2, 6, v1
	v_and_b32_e32 v1, 0xc0, v1
	s_abs_i32 s12, s11
	v_sub_u32_e32 v0, v0, v1
	v_lshlrev_b32_e32 v3, 3, v15
	v_and_b32_e32 v3, -16, v3
	s_sub_i32 s20, 0, s12
	v_add_u32_e32 v3, v2, v3
	v_and_b32_e32 v2, 3, v2
	v_and_or_b32 v2, v3, s4, v2
	s_ashr_i32 s13, s11, 31
	v_readlane_b32 s4, v254, 58
	s_xor_b32 s13, s4, s13
	s_mov_b32 s21, 0x20000000
	s_mul_i32 s20, s20, s21
	s_mul_hi_u32 s20, s21, s20
	s_add_i32 s21, s21, s20
	v_readlane_b32 s4, v254, 60
	s_mul_hi_u32 s20, s4, s21
	s_mul_i32 s21, s20, s12
	s_sub_i32 s21, s4, s21
	s_add_i32 s30, s20, 1
	s_sub_i32 s31, s21, s12
	s_cmp_ge_u32 s21, s12
	s_cselect_b32 s20, s30, s20
	s_cselect_b32 s21, s31, s21
	s_add_i32 s30, s20, 1
	s_cmp_ge_u32 s21, s12
	s_cselect_b32 s12, s30, s20
	s_lshl_b32 s10, s10, 2
	s_abs_i32 s20, s10
	s_xor_b32 s12, s12, s13
	s_sub_i32 s13, s12, s13
	s_sub_i32 s30, 0, s20
	s_mul_i32 s11, s13, s11
	v_readlane_b32 s4, v254, 59
	s_sub_i32 s11, s4, s11
	s_abs_i32 s21, s11
	s_xor_b32 s12, s11, s10
	s_ashr_i32 s12, s12, 31
	s_mov_b32 s31, 0x8000000
	s_mul_i32 s30, s30, s31
	s_mul_hi_u32 s30, s31, s30
	s_add_i32 s31, s31, s30
	s_mul_hi_u32 s30, s21, s31
	s_mul_i32 s31, s30, s20
	s_sub_i32 s21, s21, s31
	s_add_i32 s31, s30, 1
	s_sub_i32 s36, s21, s20
	s_cmp_ge_u32 s21, s20
	s_cselect_b32 s30, s31, s30
	s_cselect_b32 s21, s36, s21
	s_add_i32 s31, s30, 1
	s_cmp_ge_u32 s21, s20
	s_cselect_b32 s20, s31, s30
	s_xor_b32 s20, s20, s12
	s_sub_i32 s12, s20, s12
	v_lshrrev_b32_e32 v4, 2, v3
	v_lshlrev_b32_e32 v5, 1, v3
	s_lshl_b32 s20, s12, 2
	v_and_b32_e32 v4, 4, v4
	v_and_b32_e32 v5, 24, v5
	s_sub_i32 s9, s9, s20
	v_or3_b32 v2, v2, v4, v5
	v_lshlrev_b32_e32 v4, 5, v15
	v_ashrrev_i16_sdwa v0, v244, sext(v0) dst_sel:DWORD dst_unused:UNUSED_PAD src0_sel:DWORD src1_sel:BYTE_0
	s_min_i32 s9, s9, 4
	v_and_b32_e32 v4, 32, v4
	v_bfe_i32 v16, v0, 0, 16
	s_abs_i32 s21, s9
	v_add_lshl_u32 v0, v4, v16, 1
	v_cvt_f32_u32_e32 v1, s21
	v_lshl_add_u32 v132, v2, 12, v0
	v_lshlrev_b32_e32 v2, 2, v3
	v_and_b32_e32 v17, 0x7ffc0, v3
	v_and_b32_e32 v18, 60, v2
	v_bfe_u32 v19, v3, 4, 2
	v_or3_b32 v2, v17, v18, v19
	v_lshl_add_u32 v134, v2, 13, v0
	v_rcp_iflag_f32_e32 v0, v1
	s_sub_i32 s30, 0, s21
	s_mul_i32 s12, s12, s10
	s_sub_i32 s10, s11, s12
	v_mul_f32_e32 v0, 0x4f7ffffe, v0
	v_cvt_u32_f32_e32 v0, v0
	s_abs_i32 s12, s10
	s_xor_b32 s11, s10, s9
	s_ashr_i32 s11, s11, 31
	v_readfirstlane_b32 s31, v0
	s_mul_i32 s30, s30, s31
	s_mul_hi_u32 s30, s31, s30
	s_add_i32 s31, s31, s30
	s_mul_hi_u32 s30, s12, s31
	s_mul_i32 s31, s30, s21
	s_sub_i32 s12, s12, s31
	s_add_i32 s31, s30, 1
	s_sub_i32 s36, s12, s21
	s_cmp_ge_u32 s12, s21
	s_cselect_b32 s30, s31, s30
	s_cselect_b32 s12, s36, s12
	s_add_i32 s31, s30, 1
	s_cmp_ge_u32 s12, s21
	s_cselect_b32 s12, s31, s30
	s_abs_i32 s21, s8
	s_xor_b32 s12, s12, s11
	s_sub_i32 s12, s12, s11
	s_mul_i32 s9, s12, s9
	s_sub_i32 s9, s10, s9
	s_add_i32 s36, s20, s9
	s_sub_i32 s11, 0, s21
	s_abs_i32 s10, s13
	s_xor_b32 s9, s13, s8
	s_ashr_i32 s9, s9, 31
	s_mov_b32 s20, 0x40000000
	s_mul_i32 s11, s11, s20
	s_mul_hi_u32 s11, s20, s11
	s_add_i32 s20, s20, s11
	s_mul_hi_u32 s11, s10, s20
	s_mul_i32 s20, s11, s21
	s_sub_i32 s10, s10, s20
	s_add_i32 s20, s11, 1
	s_sub_i32 s30, s10, s21
	s_cmp_ge_u32 s10, s21
	s_cselect_b32 s11, s20, s11
	s_cselect_b32 s10, s30, s10
	s_add_i32 s20, s11, 1
	s_cmp_ge_u32 s10, s21
	s_cselect_b32 s10, s20, s11
	s_xor_b32 s10, s10, s9
	s_sub_i32 s56, s10, s9
	s_mul_i32 s8, s56, s8
	s_sub_i32 s52, s13, s8
	s_ashr_i32 s57, s56, 31
	s_ashr_i32 s53, s52, 31
	s_lshl_b64 s[8:9], s[56:57], 21
	s_add_u32 s10, s62, s8
	s_addc_u32 s11, s66, s9
	s_lshl_b64 s[8:9], s[52:53], 10
	s_add_u32 s10, s10, s8
	s_addc_u32 s11, s11, s9
	s_ashr_i32 s13, s12, 31
	s_add_u32 s20, s0, s8
	s_addc_u32 s21, s1, s9
	s_lshl_b64 s[8:9], s[12:13], 20
	s_add_u32 s76, s20, s8
	s_addc_u32 s77, s21, s9
	s_add_i32 s13, s29, 0
	s_add_i32 m0, s13, 0x10000
	s_ashr_i32 s37, s36, 31
	global_load_lds_dwordx4 v132, s[76:77]
	s_add_i32 m0, s13, 0x12000
	s_add_u32 s8, s76, 0x80000
	global_load_lds_dwordx4 v128, s[76:77]
	s_addc_u32 s9, s77, 0
	s_add_i32 m0, s13, 0x14000
	v_mov_b32_e32 v133, v193
	global_load_lds_dwordx4 v132, s[8:9]
	s_add_i32 m0, s13, 0x16000
	v_mov_b32_e32 v129, v193
	global_load_lds_dwordx4 v128, s[8:9]
	s_lshl_b64 s[8:9], s[36:37], 21
	s_add_u32 s60, s10, s8
	s_addc_u32 s61, s11, s9
	s_add_i32 s67, s13, 0x2000
	s_mov_b32 m0, s13
	s_add_u32 s8, s60, 0x100000
	global_load_lds_dwordx4 v134, s[60:61]
	s_mov_b32 m0, s67
	s_addc_u32 s9, s61, 0
	s_add_i32 s68, s13, 0x4000
	global_load_lds_dwordx4 v130, s[60:61]
	s_mov_b32 m0, s68
	s_add_i32 s69, s13, 0x6000
	global_load_lds_dwordx4 v134, s[8:9]
	s_mov_b32 m0, s69
	v_mov_b32_e32 v135, v193
	global_load_lds_dwordx4 v130, s[8:9]
	v_mov_b32_e32 v131, v193
	v_lshl_add_u64 v[6:7], s[76:77], 0, v[132:133]
	v_lshl_add_u64 v[4:5], s[76:77], 0, v[128:129]
	v_lshl_add_u64 v[2:3], s[60:61], 0, v[134:135]
	s_and_b64 vcc, exec, s[38:39]
	v_lshl_add_u64 v[0:1], s[60:61], 0, v[130:131]
	s_cbranch_vccnz .LBB0_398
	s_barrier

;     __device__ __forceinline__ bool next(int i, Unit& u) const {
;         int nM = this->nM, nN = this->nN, Z2 = this->Z2; asm volatile("" : "+s"(nM), "+s"(nN), "+s"(Z2));
;         const long L = (long)i * G + c; if (L >= nwg) return false;
;         int wgid = (int)L; { const int q = nwg / NXCD, r = nwg % NXCD, xcd = wgid % NXCD, off = wgid / NXCD; wgid = (xcd < r ? xcd * (q + 1) : r * (q + 1) + (xcd - r) * q) + off; }
;         if (rev) wgid = nwg - 1 - wgid;
;         const int per = nM * nN, z = wgid / per, rem = wgid - z * per;
;         const int nig = WGM * nN, gid = rem / nig, fm = gid * WGM, gsz = (nM - fm) < WGM ? (nM - fm) : WGM, ri = rem - gid * nig;
;         u.pm = fm + (ri % gsz); u.pn = ri / gsz; u.z1 = z / Z2; u.z2 = z - u.z1 * Z2; return true;
.LBB0_401:
	s_add_i32 s91, s91, 1
	s_mul_i32 s10, s91, s90
	s_mul_hi_u32 s11, s91, s87
	s_add_i32 s11, s11, s10
	s_mul_i32 s10, s91, s87
	s_add_u32 s10, s10, s2
	s_addc_u32 s11, s11, s33
	v_cmp_gt_i64_e32 vcc, s[10:11], v[198:199]
	s_mov_b32 s21, 8
	s_mov_b32 s9, 1
	s_mov_b32 s8, 4
	v_cmp_lt_i64_e64 s[46:47], s[10:11], v[196:197]
	s_cbranch_vccnz .LBB0_403
	s_ashr_i32 s11, s10, 31
	s_lshr_b32 s11, s11, 29
	s_add_i32 s11, s10, s11
	s_ashr_i32 s20, s11, 3
	s_and_b32 s11, s11, -8
	s_sub_i32 s10, s10, s11
	s_cmp_lt_i32 s10, 0
	s_movk_i32 s4, 0x51
	s_mul_i32 s30, s9, s21
	s_cselect_b32 s11, s4, 0x50
	s_abs_i32 s31, s30
	s_mul_i32 s10, s10, s11
	s_sub_i32 s11, 0, s31
	s_add_i32 s10, s10, s20
	s_abs_i32 s37, s10
	s_xor_b32 s20, s10, s30
	s_ashr_i32 s20, s20, 31
	s_mov_b32 s40, 0x20000000
	s_mul_i32 s11, s11, s40
	s_mul_hi_u32 s11, s40, s11
	s_add_i32 s40, s40, s11
	s_mul_hi_u32 s11, s37, s40
	s_mul_i32 s40, s11, s31
	s_sub_i32 s37, s37, s40
	s_add_i32 s40, s11, 1
	s_sub_i32 s41, s37, s31
	s_cmp_ge_u32 s37, s31
	s_cselect_b32 s11, s40, s11
	s_cselect_b32 s37, s41, s37
	s_add_i32 s40, s11, 1
	s_cmp_ge_u32 s37, s31
	s_cselect_b32 s11, s40, s11
	s_lshl_b32 s21, s21, 2
	s_abs_i32 s31, s21
	s_xor_b32 s11, s11, s20
	s_sub_i32 s11, s11, s20
	s_sub_i32 s37, 0, s31
	s_mul_i32 s20, s11, s30
	s_sub_i32 s10, s10, s20
	s_abs_i32 s30, s10
	s_xor_b32 s20, s10, s21
	s_ashr_i32 s20, s20, 31
	s_mov_b32 s40, 0x8000000
	s_mul_i32 s37, s37, s40
	s_mul_hi_u32 s37, s40, s37
	s_add_i32 s40, s40, s37
	s_mul_hi_u32 s37, s30, s40
	s_mul_i32 s40, s37, s31
	s_sub_i32 s30, s30, s40
	s_add_i32 s40, s37, 1
	s_sub_i32 s41, s30, s31
	s_cmp_ge_u32 s30, s31
	s_cselect_b32 s37, s40, s37
	s_cselect_b32 s30, s41, s30
	s_add_i32 s40, s37, 1
	s_cmp_ge_u32 s30, s31
	s_cselect_b32 s30, s40, s37
	s_xor_b32 s30, s30, s20
	s_sub_i32 s20, s30, s20
	s_lshl_b32 s30, s20, 2
	s_sub_i32 s9, s9, s30
	s_min_i32 s9, s9, 4
	s_abs_i32 s31, s9
	v_cvt_f32_u32_e32 v0, s31
	s_sub_i32 s37, 0, s31
	s_mul_i32 s20, s20, s21
	s_sub_i32 s10, s10, s20
	v_rcp_iflag_f32_e32 v0, v0
	s_abs_i32 s21, s10
	s_xor_b32 s20, s10, s9
	s_ashr_i32 s20, s20, 31
	v_mul_f32_e32 v0, 0x4f7ffffe, v0
	v_cvt_u32_f32_e32 v0, v0
	s_nop 0
	v_readfirstlane_b32 s40, v0
	s_mul_i32 s37, s37, s40
	s_mul_hi_u32 s37, s40, s37
	s_add_i32 s40, s40, s37
	s_mul_hi_u32 s37, s21, s40
	s_mul_i32 s40, s37, s31
	s_sub_i32 s21, s21, s40
	s_add_i32 s40, s37, 1
	s_sub_i32 s41, s21, s31
	s_cmp_ge_u32 s21, s31
	s_cselect_b32 s37, s40, s37
	s_cselect_b32 s21, s41, s21
	s_add_i32 s40, s37, 1
	s_cmp_ge_u32 s21, s31
	s_cselect_b32 s21, s40, s37
	s_abs_i32 s31, s8
	s_xor_b32 s21, s21, s20
	s_sub_i32 s20, s21, s20
	s_sub_i32 s21, 0, s31
	s_mul_i32 s9, s20, s9
	s_sub_i32 s9, s10, s9
	s_abs_i32 s10, s11
	s_add_i32 s30, s30, s9
	s_xor_b32 s9, s11, s8
	s_ashr_i32 s9, s9, 31
	s_mov_b32 s37, 0x40000000
	s_mul_i32 s21, s21, s37
	s_mul_hi_u32 s21, s37, s21
	s_add_i32 s37, s37, s21
	s_mul_hi_u32 s21, s10, s37
	s_mul_i32 s37, s21, s31
	s_sub_i32 s10, s10, s37
	s_add_i32 s37, s21, 1
	s_sub_i32 s40, s10, s31
	s_cmp_ge_u32 s10, s31
	s_cselect_b32 s21, s37, s21
	s_cselect_b32 s10, s40, s10
	s_add_i32 s37, s21, 1
	s_cmp_ge_u32 s10, s31
	s_cselect_b32 s10, s37, s21
	s_xor_b32 s10, s10, s9
	s_sub_i32 s44, s10, s9
	s_mul_i32 s8, s44, s8
	s_sub_i32 s48, s11, s8

; #define PG8_LAS __attribute__((address_space(3)))
; __device__ __forceinline__ int lane_id_opq() { int l; asm volatile("v_mbcnt_lo_u32_b32 %0, -1, 0\n\tv_mbcnt_hi_u32_b32 %0, -1, %0" : "=v"(l)); return l; }
; template <class Epi>
; __device__ __forceinline__ void gemm_phase(PG8_LAS unsigned char* lds, PG8_LAS unsigned char* xl, const Gemm g, const Sched& S, const Epi& E, const int wid) {
;     const int lane = lane_id_opq(), tid = wid * 64 + lane;
;     const int wr = wid >> 2, wc = wid & 3, fr = lane & 15, fq = lane >> 4;
;     const int K = g.K, nt = K / BK;
;     unsigned voffA[2], voffB[2];
; #pragma unroll
;     for (int i = 0; i < 2; ++i) { int R, C; stage_rc(tid * 16 + i * 8192, R, C); const int Rb = Epi::PERM ? ((R & ~31) + perm32(R & 31)) : R;
;         const int Ra = Epi::PERM ? ((R & ~63) + 4 * (R & 15) + ((R >> 4) & 3)) : R;
;         voffA[i] = (unsigned)(Ra * g.lda + C) * 2u; voffB[i] = (unsigned)(Rb * g.ldb + C) * 2u; }
;     const size_t kstep = (size_t)(BK * 2);
;     const size_t hstepA = (size_t)HALF * g.lda * 2, hstepB = (size_t)HALF * g.ldb * 2;
;     const unsigned ldsw = (unsigned)wid * 1024u;
;     const int aoff = lds_byte(wr * 64 + fr, fq * 8), boff = lds_byte(wc * 32 + fr, fq * 8);
;     ...
;     Unit cur, nxt; int ui = 0;
;     if (!S.next(0, cur)) return;
.LBB0_415:
	v_readlane_b32 s0, v254, 13
	s_add_i32 s0, s87, s0
	v_readlane_b32 s90, v252, 30
	v_readlane_b32 s72, v252, 34
	v_readlane_b32 s76, v252, 36
	v_readlane_b32 s88, v252, 38
	s_mov_b32 s9, 8
	s_mov_b32 s10, 1
	s_mov_b32 s8, 4
	s_cmpk_gt_i32 s0, 0x27f
	v_readlane_b32 s91, v252, 31
	v_readlane_b32 s73, v252, 35
	v_readlane_b32 s77, v252, 37
	v_readlane_b32 s89, v252, 39
	v_mbcnt_lo_u32_b32 v8, -1, 0
	v_mbcnt_hi_u32_b32 v8, -1, v8
	s_cbranch_scc1 .LBB0_435
; #define PG8_BAR __builtin_amdgcn_s_barrier()
;     __device__ __forceinline__ bool next(int i, Unit& u) const {
;         int nM = this->nM, nN = this->nN, Z2 = this->Z2; asm volatile("" : "+s"(nM), "+s"(nN), "+s"(Z2));
; template <class Epi>
; __device__ __forceinline__ void gemm_phase(PG8_LAS unsigned char* lds, PG8_LAS unsigned char* xl, const Gemm g, const Sched& S, const Epi& E, const int wid) {
;     const int lane = lane_id_opq(), tid = wid * 64 + lane;
;     const int wr = wid >> 2, wc = wid & 3, fr = lane & 15, fq = lane >> 4;
;     const int K = g.K, nt = K / BK;
;     unsigned voffA[2], voffB[2];
; #pragma unroll
;     for (int i = 0; i < 2; ++i) { int R, C; stage_rc(tid * 16 + i * 8192, R, C); const int Rb = Epi::PERM ? ((R & ~31) + perm32(R & 31)) : R;
;         const int Ra = Epi::PERM ? ((R & ~63) + 4 * (R & 15) + ((R >> 4) & 3)) : R;
;         voffA[i] = (unsigned)(Ra * g.lda + C) * 2u; voffB[i] = (unsigned)(Rb * g.ldb + C) * 2u; }
;     const size_t kstep = (size_t)(BK * 2);
;     const size_t hstepA = (size_t)HALF * g.lda * 2, hstepB = (size_t)HALF * g.ldb * 2;
;     const unsigned ldsw = (unsigned)wid * 1024u;
;     const int aoff = lds_byte(wr * 64 + fr, fq * 8), boff = lds_byte(wc * 32 + fr, fq * 8);
;     ...
;     Unit cur, nxt; int ui = 0;
;     if (!S.next(0, cur)) return;
;     Acc acc;
; #pragma unroll
;     for (int a = 0; a < 2; ++a)
; #pragma unroll
;         for (int b = 0; b < 2; ++b)
; #pragma unroll
;             for (int m = 0; m < 4; ++m)
; #pragma unroll
;                 for (int n = 0; n < 2; ++n) acc[a][b][m][n] = (f32x4){0.f, 0.f, 0.f, 0.f};
;     bf16x8 At[4][2], B0[2][2], B1[2][2];
;     float prc[8];
; #pragma unroll
;     for (int k = 0; k < 8; ++k) prc[k] = 1.0f;
;     if constexpr (Epi::PRE) { const float* pb = E.pre_base(cur) + wr * 64 + 4 * fr;
; #pragma unroll
;         for (int k = 0; k < 8; ++k) prc[k] = pb[(k >> 2) * HALF + (k & 3)]; }
;     const char* cA = a_tile(g, cur); const char* cB = b_tile(g, cur);
;     PG8_STAGE(PG8_SB(0, 0), cB, voffB); PG8_STAGE(PG8_SB(0, 1), cB + hstepB, voffB); PG8_STAGE(PG8_SA(0, 0), cA, voffA); PG8_STAGE(PG8_SA(0, 1), cA + hstepA, voffA);
;     if (wr == 1) PG8_BAR;
;     PG8_WAIT_V(2); PG8_BAR;
;     PG8_STAGE(PG8_SB(1, 0), cB + kstep, voffB); PG8_STAGE(PG8_SA(1, 0), cA + kstep, voffA); PG8_STAGE(PG8_SB(1, 1), cB + hstepB + kstep, voffB);
;     PG8_WAIT_V(6); PG8_BAR;
	v_lshlrev_b32_e32 v10, 4, v8
	v_add_u32_e32 v0, s29, v10
	v_add_u32_e32 v1, 0x2000, v0
	v_ashrrev_i32_e32 v2, 31, v1
	v_lshrrev_b32_e32 v2, 22, v2
	v_add_u32_e32 v2, v1, v2
	v_ashrrev_i32_e32 v9, 10, v2
	v_mul_i32_i24_e32 v2, 0x400, v9
	v_sub_u32_e32 v1, v1, v2
	v_lshrrev_b32_e32 v2, 4, v1
	v_bitop3_b32 v1, v2, v1, 32 bitop3:0x6c
	v_ashrrev_i32_e32 v2, 31, v1
	v_lshrrev_b32_e32 v2, 26, v2
	v_add_u32_e32 v2, v1, v2
	v_ashrrev_i32_e32 v3, 6, v2
	v_lshlrev_b32_e32 v4, 3, v9
	v_and_b32_e32 v2, 0xffc0, v2
	v_and_b32_e32 v4, -16, v4
	v_sub_u32_e32 v1, v1, v2
	v_add_u32_e32 v4, v3, v4
	v_lshrrev_b16_e32 v2, 7, v1
	v_and_b32_e32 v3, 3, v3
	s_mov_b32 s4, 0x7ffe0
	v_lshrrev_b32_e32 v5, 2, v4
	v_lshlrev_b32_e32 v6, 1, v4
	v_and_b32_e32 v2, 1, v2
	v_and_or_b32 v3, v4, s4, v3
	v_and_b32_e32 v5, 4, v5
	v_and_b32_e32 v6, 24, v6
	v_add_u16_e32 v1, v1, v2
	v_or3_b32 v3, v3, v5, v6
	v_lshlrev_b32_e32 v5, 5, v9
	v_ashrrev_i16_sdwa v1, v244, sext(v1) dst_sel:DWORD dst_unused:UNUSED_PAD src0_sel:DWORD src1_sel:BYTE_0
	v_lshlrev_b32_e32 v2, 2, v4
	v_and_b32_e32 v5, 32, v5
	v_bfe_i32 v11, v1, 0, 16
	v_and_b32_e32 v12, 0xfffc0, v4
	v_and_b32_e32 v13, 60, v2
	v_bfe_u32 v14, v4, 4, 2
	v_add_lshl_u32 v1, v5, v11, 1
	v_or3_b32 v2, v12, v13, v14
	v_lshl_add_u32 v128, v3, 13, v1
	v_lshl_add_u32 v130, v2, 12, v1
	v_ashrrev_i32_e32 v1, 31, v0
	v_lshrrev_b32_e32 v1, 22, v1
	v_add_u32_e32 v1, v0, v1
	v_ashrrev_i32_e32 v15, 10, v1
	v_mul_i32_i24_e32 v1, 0x400, v15
	s_waitcnt lgkmcnt(0)
	s_add_u32 s1, s50, 0x6000000
	v_sub_u32_e32 v0, v0, v1
	s_addc_u32 s62, s51, 0
	v_lshrrev_b32_e32 v1, 4, v0
	s_add_u32 s66, s50, 0x16001000
	v_bitop3_b32 v0, v1, v0, 32 bitop3:0x6c
	s_addc_u32 s67, s51, 0
	v_ashrrev_i32_e32 v1, 31, v0
	s_ashr_i32 s68, s0, 31
	v_lshrrev_b32_e32 v1, 26, v1
	s_lshr_b32 s11, s68, 29
	v_add_u32_e32 v1, v0, v1
	v_lshlrev_b32_e32 v3, 3, v15
	s_add_i32 s11, s0, s11
	v_ashrrev_i32_e32 v2, 6, v1
	v_and_b32_e32 v3, -16, v3
	s_ashr_i32 s12, s11, 3
	s_and_b32 s11, s11, -8
	v_add_u32_e32 v3, v2, v3
	v_and_b32_e32 v2, 3, v2
	s_sub_i32 s11, s0, s11
	v_and_or_b32 v2, v3, s4, v2
	s_cmp_lt_i32 s11, 0
	s_movk_i32 s4, 0x51
	s_mul_i32 s20, s9, s10
	v_and_b32_e32 v1, 0xc0, v1
	s_cselect_b32 s13, s4, 0x50
	s_abs_i32 s21, s20
	v_sub_u32_e32 v0, v0, v1
	s_sub_i32 s30, 0, s21
	s_mul_i32 s11, s11, s13
	s_add_i32 s11, s11, s12
	s_abs_i32 s13, s11
	s_xor_b32 s12, s11, s20
	s_ashr_i32 s12, s12, 31
	v_lshrrev_b32_e32 v4, 2, v3
	v_lshlrev_b32_e32 v5, 1, v3
	v_and_b32_e32 v4, 4, v4
	s_mov_b32 s31, 0x20000000
	s_mul_i32 s30, s30, s31
	s_mul_hi_u32 s30, s31, s30
	s_add_i32 s31, s31, s30
	s_mul_hi_u32 s30, s13, s31
	s_mul_i32 s31, s30, s21
	s_sub_i32 s13, s13, s31
	s_add_i32 s31, s30, 1
	s_sub_i32 s36, s13, s21
	s_cmp_ge_u32 s13, s21
	s_cselect_b32 s30, s31, s30
	s_cselect_b32 s13, s36, s13
	s_add_i32 s31, s30, 1
	s_cmp_ge_u32 s13, s21
	s_cselect_b32 s13, s31, s30
	s_lshl_b32 s10, s10, 2
	s_abs_i32 s21, s10
	s_xor_b32 s13, s13, s12
	s_sub_i32 s13, s13, s12
	s_sub_i32 s30, 0, s21
	s_mul_i32 s12, s13, s20
	s_sub_i32 s11, s11, s12
	s_abs_i32 s20, s11
	s_xor_b32 s12, s11, s10
	s_ashr_i32 s12, s12, 31
	v_and_b32_e32 v5, 24, v5
	s_mov_b32 s31, 0x40000000
	s_mul_i32 s30, s30, s31
	s_mul_hi_u32 s30, s31, s30
	s_add_i32 s31, s31, s30
	s_mul_hi_u32 s30, s20, s31
	s_mul_i32 s31, s30, s21
	s_sub_i32 s20, s20, s31
	s_add_i32 s31, s30, 1
	s_sub_i32 s36, s20, s21
	s_cmp_ge_u32 s20, s21
	s_cselect_b32 s30, s31, s30
	s_cselect_b32 s20, s36, s20
	s_add_i32 s31, s30, 1
	s_cmp_ge_u32 s20, s21
	s_cselect_b32 s20, s31, s30
	s_xor_b32 s20, s20, s12
	s_sub_i32 s12, s20, s12
	s_lshl_b32 s20, s12, 2
	s_sub_i32 s9, s9, s20
	v_or3_b32 v2, v2, v4, v5
	v_lshlrev_b32_e32 v4, 5, v15
	v_ashrrev_i16_sdwa v0, v244, sext(v0) dst_sel:DWORD dst_unused:UNUSED_PAD src0_sel:DWORD src1_sel:BYTE_0
	s_min_i32 s9, s9, 4
	v_and_b32_e32 v4, 32, v4
	v_bfe_i32 v16, v0, 0, 16
	s_abs_i32 s21, s9
	v_add_lshl_u32 v0, v4, v16, 1
	v_cvt_f32_u32_e32 v1, s21
	v_lshl_add_u32 v132, v2, 13, v0
	v_lshlrev_b32_e32 v2, 2, v3
	v_and_b32_e32 v17, 0xfffc0, v3
	v_and_b32_e32 v18, 60, v2
	v_bfe_u32 v19, v3, 4, 2
	v_or3_b32 v2, v17, v18, v19
	v_lshl_add_u32 v134, v2, 12, v0
	v_rcp_iflag_f32_e32 v0, v1
	s_sub_i32 s30, 0, s21
	s_mul_i32 s12, s12, s10
	s_sub_i32 s10, s11, s12
	v_mul_f32_e32 v0, 0x4f7ffffe, v0
	v_cvt_u32_f32_e32 v0, v0
	s_abs_i32 s12, s10
	s_xor_b32 s11, s10, s9
	s_ashr_i32 s11, s11, 31
	v_readfirstlane_b32 s31, v0
	s_mul_i32 s30, s30, s31
	s_mul_hi_u32 s30, s31, s30
	s_add_i32 s31, s31, s30
	s_mul_hi_u32 s30, s12, s31
	s_mul_i32 s31, s30, s21
	s_sub_i32 s12, s12, s31
	s_add_i32 s31, s30, 1
	s_sub_i32 s36, s12, s21
	s_cmp_ge_u32 s12, s21
	s_cselect_b32 s30, s31, s30
	s_cselect_b32 s12, s36, s12
	s_add_i32 s31, s30, 1
	s_cmp_ge_u32 s12, s21
	s_cselect_b32 s12, s31, s30
	s_abs_i32 s21, s8
	s_xor_b32 s12, s12, s11
	s_sub_i32 s12, s12, s11
	s_sub_i32 s11, 0, s21
	s_mul_i32 s9, s12, s9
	s_sub_i32 s9, s10, s9
	s_abs_i32 s10, s13
	s_add_i32 s20, s20, s9
	s_xor_b32 s9, s13, s8
	s_ashr_i32 s9, s9, 31
	s_mov_b32 s30, 0x40000000
	s_mul_i32 s11, s11, s30
	s_mul_hi_u32 s11, s30, s11
	s_add_i32 s30, s30, s11
	s_mul_hi_u32 s11, s10, s30
	s_mul_i32 s30, s11, s21
	s_sub_i32 s10, s10, s30
	s_add_i32 s30, s11, 1
	s_sub_i32 s31, s10, s21
	s_cmp_ge_u32 s10, s21
	s_cselect_b32 s11, s30, s11
	s_cselect_b32 s10, s31, s10
	s_add_i32 s30, s11, 1
	s_cmp_ge_u32 s10, s21
	s_cselect_b32 s10, s30, s11
	s_xor_b32 s10, s10, s9
	s_sub_i32 s48, s10, s9
	s_mul_i32 s8, s48, s8
	s_sub_i32 s44, s13, s8
	s_ashr_i32 s45, s44, 31
	s_ashr_i32 s49, s48, 31
	s_lshl_b64 s[8:9], s[44:45], 10
	s_add_u32 s30, s1, s8
	s_addc_u32 s31, s62, s9
	s_ashr_i32 s13, s12, 31
	s_lshl_b64 s[10:11], s[48:49], 21
	s_add_u32 s10, s66, s10
	s_addc_u32 s11, s67, s11
	s_add_u32 s10, s10, s8
	s_addc_u32 s11, s11, s9
	s_lshl_b64 s[8:9], s[12:13], 21
	s_add_u32 s60, s10, s8
	s_addc_u32 s61, s11, s9
	s_add_i32 s13, s29, 0
	s_add_i32 m0, s13, 0x10000
	s_ashr_i32 s21, s20, 31
	global_load_lds_dwordx4 v132, s[60:61]
	s_add_i32 m0, s13, 0x12000
	s_add_u32 s8, s60, 0x100000
	global_load_lds_dwordx4 v128, s[60:61]
	s_addc_u32 s9, s61, 0
	s_add_i32 m0, s13, 0x14000
	v_mov_b32_e32 v133, v193
	global_load_lds_dwordx4 v132, s[8:9]
	s_add_i32 m0, s13, 0x16000
	v_mov_b32_e32 v129, v193
	global_load_lds_dwordx4 v128, s[8:9]
	s_lshl_b64 s[8:9], s[20:21], 20
	s_add_u32 s58, s30, s8
	s_addc_u32 s59, s31, s9
	s_add_i32 s69, s13, 0x2000
	s_mov_b32 m0, s13
	s_add_u32 s8, s58, 0x80000
	global_load_lds_dwordx4 v134, s[58:59]
	s_mov_b32 m0, s69
	s_addc_u32 s9, s59, 0
	s_add_i32 s70, s13, 0x4000
	global_load_lds_dwordx4 v130, s[58:59]
	s_mov_b32 m0, s70
	s_add_i32 s71, s13, 0x6000
	global_load_lds_dwordx4 v134, s[8:9]
	s_mov_b32 m0, s71
	v_mov_b32_e32 v135, v193
	global_load_lds_dwordx4 v130, s[8:9]
	v_mov_b32_e32 v131, v193
	v_lshl_add_u64 v[6:7], s[60:61], 0, v[132:133]
	v_lshl_add_u64 v[4:5], s[60:61], 0, v[128:129]
	v_lshl_add_u64 v[2:3], s[58:59], 0, v[134:135]
	s_and_b64 vcc, exec, s[38:39]
	v_lshl_add_u64 v[0:1], s[58:59], 0, v[130:131]
	s_cbranch_vccnz .LBB0_418
	s_barrier

;     __device__ __forceinline__ bool next(int i, Unit& u) const {
;         int nM = this->nM, nN = this->nN, Z2 = this->Z2; asm volatile("" : "+s"(nM), "+s"(nN), "+s"(Z2));
;         const long L = (long)i * G + c; if (L >= nwg) return false;
;         int wgid = (int)L; { const int q = nwg / NXCD, r = nwg % NXCD, xcd = wgid % NXCD, off = wgid / NXCD; wgid = (xcd < r ? xcd * (q + 1) : r * (q + 1) + (xcd - r) * q) + off; }
;         if (rev) wgid = nwg - 1 - wgid;
;         const int per = nM * nN, z = wgid / per, rem = wgid - z * per;
;         const int nig = WGM * nN, gid = rem / nig, fm = gid * WGM, gsz = (nM - fm) < WGM ? (nM - fm) : WGM, ri = rem - gid * nig;
;         u.pm = fm + (ri % gsz); u.pn = ri / gsz; u.z1 = z / Z2; u.z2 = z - u.z1 * Z2; return true;
.LBB0_421:
	s_add_i32 s93, s93, 1
	s_mul_i32 s10, s93, s92
	s_mul_hi_u32 s11, s93, s87
	s_add_i32 s11, s11, s10
	s_mul_i32 s10, s93, s87
	s_add_u32 s10, s10, s0
	s_addc_u32 s11, s11, s68
	v_cmp_gt_i64_e32 vcc, s[10:11], v[198:199]
	s_mov_b32 s9, 8
	s_mov_b32 s21, 1
	s_mov_b32 s8, 4
	v_cmp_lt_i64_e64 s[46:47], s[10:11], v[196:197]
	s_cbranch_vccnz .LBB0_423
	s_ashr_i32 s11, s10, 31
	s_lshr_b32 s11, s11, 29
	s_add_i32 s11, s10, s11
	s_ashr_i32 s30, s11, 3
	s_and_b32 s11, s11, -8
	s_sub_i32 s10, s10, s11
	s_cmp_lt_i32 s10, 0
	s_movk_i32 s4, 0x51
	s_mul_i32 s31, s9, s21
	s_cselect_b32 s11, s4, 0x50
	s_abs_i32 s36, s31
	s_mul_i32 s10, s10, s11
	s_sub_i32 s11, 0, s36
	s_add_i32 s10, s10, s30
	s_abs_i32 s37, s10
	s_xor_b32 s30, s10, s31
	s_ashr_i32 s30, s30, 31
	s_mov_b32 s40, 0x20000000
	s_mul_i32 s11, s11, s40
	s_mul_hi_u32 s11, s40, s11
	s_add_i32 s40, s40, s11
	s_mul_hi_u32 s11, s37, s40
	s_mul_i32 s40, s11, s36
	s_sub_i32 s37, s37, s40
	s_add_i32 s40, s11, 1
	s_sub_i32 s41, s37, s36
	s_cmp_ge_u32 s37, s36
	s_cselect_b32 s11, s40, s11
	s_cselect_b32 s37, s41, s37
	s_add_i32 s40, s11, 1
	s_cmp_ge_u32 s37, s36
	s_cselect_b32 s11, s40, s11
	s_lshl_b32 s21, s21, 2
	s_abs_i32 s36, s21
	s_xor_b32 s11, s11, s30
	s_sub_i32 s11, s11, s30
	s_sub_i32 s37, 0, s36
	s_mul_i32 s30, s11, s31
	s_sub_i32 s10, s10, s30
	s_abs_i32 s31, s10
	s_xor_b32 s30, s10, s21
	s_ashr_i32 s30, s30, 31
	s_mov_b32 s40, 0x40000000
	s_mul_i32 s37, s37, s40
	s_mul_hi_u32 s37, s40, s37
	s_add_i32 s40, s40, s37
	s_mul_hi_u32 s37, s31, s40
	s_mul_i32 s40, s37, s36
	s_sub_i32 s31, s31, s40
	s_add_i32 s40, s37, 1
	s_sub_i32 s41, s31, s36
	s_cmp_ge_u32 s31, s36
	s_cselect_b32 s37, s40, s37
	s_cselect_b32 s31, s41, s31
	s_add_i32 s40, s37, 1
	s_cmp_ge_u32 s31, s36
	s_cselect_b32 s31, s40, s37
	s_xor_b32 s31, s31, s30
	s_sub_i32 s30, s31, s30
	s_lshl_b32 s31, s30, 2
	s_sub_i32 s9, s9, s31
	s_min_i32 s9, s9, 4
	s_abs_i32 s36, s9
	v_cvt_f32_u32_e32 v0, s36
	s_sub_i32 s37, 0, s36
	s_mul_i32 s30, s30, s21
	s_sub_i32 s10, s10, s30
	v_rcp_iflag_f32_e32 v0, v0
	s_abs_i32 s30, s10
	s_xor_b32 s21, s10, s9
	s_ashr_i32 s21, s21, 31
	v_mul_f32_e32 v0, 0x4f7ffffe, v0
	v_cvt_u32_f32_e32 v0, v0
	s_nop 0
	v_readfirstlane_b32 s40, v0
	s_mul_i32 s37, s37, s40
	s_mul_hi_u32 s37, s40, s37
	s_add_i32 s40, s40, s37
	s_mul_hi_u32 s37, s30, s40
	s_mul_i32 s40, s37, s36
	s_sub_i32 s30, s30, s40
	s_add_i32 s40, s37, 1
	s_sub_i32 s41, s30, s36
	s_cmp_ge_u32 s30, s36
	s_cselect_b32 s37, s40, s37
	s_cselect_b32 s30, s41, s30
	s_add_i32 s40, s37, 1
	s_cmp_ge_u32 s30, s36
	s_cselect_b32 s30, s40, s37
	s_abs_i32 s37, s8
	s_xor_b32 s30, s30, s21
	s_sub_i32 s30, s30, s21
	s_mul_i32 s9, s30, s9
	s_sub_i32 s9, s10, s9
	s_add_i32 s36, s31, s9
	s_sub_i32 s21, 0, s37
	s_abs_i32 s10, s11
	s_xor_b32 s9, s11, s8
	s_ashr_i32 s9, s9, 31
	s_mov_b32 s31, 0x40000000
	s_mul_i32 s21, s21, s31
	s_mul_hi_u32 s21, s31, s21
	s_add_i32 s31, s31, s21
	s_mul_hi_u32 s21, s10, s31
	s_mul_i32 s31, s21, s37
	s_sub_i32 s10, s10, s31
	s_add_i32 s31, s21, 1
	s_sub_i32 s40, s10, s37
	s_cmp_ge_u32 s10, s37
	s_cselect_b32 s21, s31, s21
	s_cselect_b32 s10, s40, s10
	s_add_i32 s31, s21, 1
	s_cmp_ge_u32 s10, s37
	s_cselect_b32 s10, s31, s21
	s_xor_b32 s10, s10, s9
	s_sub_i32 s50, s10, s9
	s_mul_i32 s8, s50, s8
	s_sub_i32 s52, s11, s8

; #define PG8_LAS __attribute__((address_space(3)))
; __device__ __forceinline__ int lane_id_opq() { int l; asm volatile("v_mbcnt_lo_u32_b32 %0, -1, 0\n\tv_mbcnt_hi_u32_b32 %0, -1, %0" : "=v"(l)); return l; }
; template <class Epi>
; __device__ __forceinline__ void gemm_phase(PG8_LAS unsigned char* lds, PG8_LAS unsigned char* xl, const Gemm g, const Sched& S, const Epi& E, const int wid) {
;     const int lane = lane_id_opq(), tid = wid * 64 + lane;
;     const int wr = wid >> 2, wc = wid & 3, fr = lane & 15, fq = lane >> 4;
;     const int K = g.K, nt = K / BK;
;     unsigned voffA[2], voffB[2];
; #pragma unroll
;     for (int i = 0; i < 2; ++i) { int R, C; stage_rc(tid * 16 + i * 8192, R, C); const int Rb = Epi::PERM ? ((R & ~31) + perm32(R & 31)) : R;
;         const int Ra = Epi::PERM ? ((R & ~63) + 4 * (R & 15) + ((R >> 4) & 3)) : R;
;         voffA[i] = (unsigned)(Ra * g.lda + C) * 2u; voffB[i] = (unsigned)(Rb * g.ldb + C) * 2u; }
;     const size_t kstep = (size_t)(BK * 2);
;     const size_t hstepA = (size_t)HALF * g.lda * 2, hstepB = (size_t)HALF * g.ldb * 2;
;     const unsigned ldsw = (unsigned)wid * 1024u;
;     const int aoff = lds_byte(wr * 64 + fr, fq * 8), boff = lds_byte(wc * 32 + fr, fq * 8);
;     ...
;     Unit cur, nxt; int ui = 0;
;     if (!S.next(0, cur)) return;
.LBB0_498:
	v_readlane_b32 s4, v254, 34
	v_readlane_b32 s5, v254, 35
	s_mov_b32 s11, 8
	s_mov_b32 s10, 1
	v_cndmask_b32_e64 v0, 0, 1, s[4:5]
	v_cmp_ne_u32_e64 s[8:9], 1, v0
	s_mov_b32 s12, 1
	s_andn2_b64 vcc, exec, s[4:5]
	v_writelane_b32 v252, s8, 46
	v_mbcnt_lo_u32_b32 v8, -1, 0
	v_mbcnt_hi_u32_b32 v8, -1, v8
	s_nop 1
	v_writelane_b32 v252, s9, 47
	s_cbranch_vccnz .LBB0_516
; #define PG8_BAR __builtin_amdgcn_s_barrier()
;     __device__ __forceinline__ bool next(int i, Unit& u) const {
;         int nM = this->nM, nN = this->nN, Z2 = this->Z2; asm volatile("" : "+s"(nM), "+s"(nN), "+s"(Z2));
; template <class Epi>
; __device__ __forceinline__ void gemm_phase(PG8_LAS unsigned char* lds, PG8_LAS unsigned char* xl, const Gemm g, const Sched& S, const Epi& E, const int wid) {
;     const int lane = lane_id_opq(), tid = wid * 64 + lane;
;     const int wr = wid >> 2, wc = wid & 3, fr = lane & 15, fq = lane >> 4;
;     const int K = g.K, nt = K / BK;
;     unsigned voffA[2], voffB[2];
; #pragma unroll
;     for (int i = 0; i < 2; ++i) { int R, C; stage_rc(tid * 16 + i * 8192, R, C); const int Rb = Epi::PERM ? ((R & ~31) + perm32(R & 31)) : R;
;         const int Ra = Epi::PERM ? ((R & ~63) + 4 * (R & 15) + ((R >> 4) & 3)) : R;
;         voffA[i] = (unsigned)(Ra * g.lda + C) * 2u; voffB[i] = (unsigned)(Rb * g.ldb + C) * 2u; }
;     const size_t kstep = (size_t)(BK * 2);
;     const size_t hstepA = (size_t)HALF * g.lda * 2, hstepB = (size_t)HALF * g.ldb * 2;
;     const unsigned ldsw = (unsigned)wid * 1024u;
;     const int aoff = lds_byte(wr * 64 + fr, fq * 8), boff = lds_byte(wc * 32 + fr, fq * 8);
;     ...
;     Unit cur, nxt; int ui = 0;
;     if (!S.next(0, cur)) return;
;     Acc acc;
; #pragma unroll
;     for (int a = 0; a < 2; ++a)
; #pragma unroll
;         for (int b = 0; b < 2; ++b)
; #pragma unroll
;             for (int m = 0; m < 4; ++m)
; #pragma unroll
;                 for (int n = 0; n < 2; ++n) acc[a][b][m][n] = (f32x4){0.f, 0.f, 0.f, 0.f};
;     bf16x8 At[4][2], B0[2][2], B1[2][2];
;     float prc[8];
; #pragma unroll
;     for (int k = 0; k < 8; ++k) prc[k] = 1.0f;
;     if constexpr (Epi::PRE) { const float* pb = E.pre_base(cur) + wr * 64 + 4 * fr;
; #pragma unroll
;         for (int k = 0; k < 8; ++k) prc[k] = pb[(k >> 2) * HALF + (k & 3)]; }
;     const char* cA = a_tile(g, cur); const char* cB = b_tile(g, cur);
;     PG8_STAGE(PG8_SB(0, 0), cB, voffB); PG8_STAGE(PG8_SB(0, 1), cB + hstepB, voffB); PG8_STAGE(PG8_SA(0, 0), cA, voffA); PG8_STAGE(PG8_SA(0, 1), cA + hstepA, voffA);
;     if (wr == 1) PG8_BAR;
;     PG8_WAIT_V(2); PG8_BAR;
;     PG8_STAGE(PG8_SB(1, 0), cB + kstep, voffB); PG8_STAGE(PG8_SA(1, 0), cA + kstep, voffA); PG8_STAGE(PG8_SB(1, 1), cB + hstepB + kstep, voffB);
;     PG8_WAIT_V(6); PG8_BAR;
	v_lshlrev_b32_e32 v9, 4, v8
	v_add_u32_e32 v0, s29, v9
	v_add_u32_e32 v1, 0x2000, v0
	v_ashrrev_i32_e32 v2, 31, v1
	v_lshrrev_b32_e32 v2, 22, v2
	v_add_u32_e32 v2, v1, v2
	v_ashrrev_i32_e32 v2, 10, v2
	v_mul_i32_i24_e32 v3, 0x400, v2
	v_sub_u32_e32 v1, v1, v3
	v_lshrrev_b32_e32 v3, 4, v1
	v_bitop3_b32 v1, v3, v1, 32 bitop3:0x6c
	v_ashrrev_i32_e32 v3, 31, v1
	v_lshrrev_b32_e32 v3, 26, v3
	v_add_u32_e32 v3, v1, v3
	v_ashrrev_i32_e32 v4, 6, v3
	v_and_b32_e32 v3, 0xffc0, v3
	v_sub_u32_e32 v1, v1, v3
	v_lshlrev_b32_e32 v5, 3, v2
	v_lshrrev_b16_e32 v3, 7, v1
	v_and_b32_e32 v5, -16, v5
	v_and_b32_e32 v3, 1, v3
	v_add_u32_e32 v5, v4, v5
	v_add_u16_e32 v1, v1, v3
	v_and_b32_e32 v4, 3, v4
	s_mov_b32 s4, 0x7fffe0
	v_lshrrev_b32_e32 v6, 2, v5
	v_lshlrev_b32_e32 v7, 1, v5
	v_lshlrev_b32_e32 v2, 5, v2
	v_ashrrev_i16_sdwa v1, v244, sext(v1) dst_sel:DWORD dst_unused:UNUSED_PAD src0_sel:DWORD src1_sel:BYTE_0
	v_and_or_b32 v4, v5, s4, v4
	v_and_b32_e32 v6, 4, v6
	v_and_b32_e32 v7, 24, v7
	v_and_b32_e32 v2, 32, v2
	v_bfe_i32 v1, v1, 0, 16
	v_or3_b32 v4, v4, v6, v7
	v_add_lshl_u32 v1, v2, v1, 1
	v_lshlrev_b32_e32 v3, 2, v5
	v_lshl_add_u32 v210, v4, 9, v1
	v_and_b32_e32 v2, 0x7fffc0, v5
	v_and_b32_e32 v3, 60, v3
	v_bfe_u32 v4, v5, 4, 2
	v_or3_b32 v2, v2, v3, v4
	v_lshl_add_u32 v212, v2, 9, v1
	v_ashrrev_i32_e32 v1, 31, v0
	v_lshrrev_b32_e32 v1, 22, v1
	v_add_u32_e32 v1, v0, v1
	v_ashrrev_i32_e32 v1, 10, v1
	v_mul_i32_i24_e32 v2, 0x400, v1
	v_sub_u32_e32 v0, v0, v2
	v_lshrrev_b32_e32 v2, 4, v0
	v_bitop3_b32 v0, v2, v0, 32 bitop3:0x6c
	v_ashrrev_i32_e32 v2, 31, v0
	v_lshrrev_b32_e32 v2, 26, v2
	v_add_u32_e32 v2, v0, v2
	v_lshlrev_b32_e32 v4, 3, v1
	v_ashrrev_i32_e32 v3, 6, v2
	v_and_b32_e32 v4, -16, v4
	v_add_u32_e32 v4, v3, v4
	s_add_u32 s8, s58, 0xaa00000
	v_and_b32_e32 v3, 3, v3
	v_lshrrev_b32_e32 v5, 2, v4
	v_lshlrev_b32_e32 v6, 1, v4
	s_mul_i32 s13, s10, s12
	s_addc_u32 s9, s59, 0
	v_and_or_b32 v3, v4, s4, v3
	v_and_b32_e32 v5, 4, v5
	v_and_b32_e32 v6, 24, v6
	s_abs_i32 s20, s13
	v_or3_b32 v3, v3, v5, v6
	v_cvt_f32_u32_e32 v5, s20
	v_and_b32_e32 v2, 0xc0, v2
	v_sub_u32_e32 v0, v0, v2
	v_lshlrev_b32_e32 v1, 5, v1
	v_rcp_iflag_f32_e32 v2, v5
	v_ashrrev_i16_sdwa v0, v244, sext(v0) dst_sel:DWORD dst_unused:UNUSED_PAD src0_sel:DWORD src1_sel:BYTE_0
	v_and_b32_e32 v1, 32, v1
	v_bfe_i32 v0, v0, 0, 16
	v_add_lshl_u32 v0, v1, v0, 1
	v_mul_f32_e32 v1, 0x4f7ffffe, v2
	v_cvt_u32_f32_e32 v1, v1
	s_sub_i32 s36, 0, s20
	s_ashr_i32 s21, s13, 31
	v_readlane_b32 s4, v254, 61
	v_readfirstlane_b32 s37, v1
	s_mul_i32 s36, s36, s37
	s_mul_hi_u32 s36, s37, s36
	s_xor_b32 s21, s4, s21
	s_add_i32 s37, s37, s36
	v_readlane_b32 s4, v254, 63
	s_mul_hi_u32 s36, s4, s37
	s_mul_i32 s37, s36, s20
	s_sub_i32 s37, s4, s37
	s_add_i32 s40, s36, 1
	s_sub_i32 s41, s37, s20
	s_cmp_ge_u32 s37, s20
	s_cselect_b32 s36, s40, s36
	s_cselect_b32 s37, s41, s37
	s_add_i32 s40, s36, 1
	s_cmp_ge_u32 s37, s20
	s_cselect_b32 s20, s40, s36
	s_abs_i32 s36, s11
	s_sub_i32 s40, 0, s36
	s_xor_b32 s20, s20, s21
	s_sub_i32 s20, s20, s21
	s_abs_i32 s37, s20
	s_xor_b32 s21, s20, s11
	s_ashr_i32 s21, s21, 31
	v_readlane_b32 s4, v254, 62
	v_lshl_add_u32 v214, v3, 9, v0
	v_lshlrev_b32_e32 v3, 2, v4
	s_mov_b32 s41, 0x20000000
	s_mul_i32 s40, s40, s41
	s_mul_hi_u32 s40, s41, s40
	s_add_i32 s41, s41, s40
	s_mul_hi_u32 s40, s37, s41
	s_mul_i32 s41, s40, s36
	s_sub_i32 s37, s37, s41
	s_add_i32 s41, s40, 1
	s_sub_i32 s42, s37, s36
	s_cmp_ge_u32 s37, s36
	s_cselect_b32 s40, s41, s40
	s_cselect_b32 s37, s42, s37
	s_add_i32 s41, s40, 1
	s_cmp_ge_u32 s37, s36
	s_cselect_b32 s36, s41, s40
	s_lshl_b32 s12, s12, 2
	s_abs_i32 s37, s12
	s_xor_b32 s36, s36, s21
	s_sub_i32 s50, s36, s21
	s_mul_i32 s11, s50, s11
	s_sub_i32 s21, 0, s37
	s_sub_i32 s52, s20, s11
	s_mul_i32 s20, s20, s13
	s_sub_i32 s11, s4, s20
	s_abs_i32 s20, s11
	s_xor_b32 s13, s11, s12
	s_mov_b32 s36, 0x40000000
	s_mul_i32 s21, s21, s36
	s_mul_hi_u32 s21, s36, s21
	s_add_i32 s36, s36, s21
	s_mul_hi_u32 s21, s20, s36
	s_mul_i32 s36, s21, s37
	s_sub_i32 s20, s20, s36
	s_ashr_i32 s13, s13, 31
	s_add_i32 s36, s21, 1
	s_sub_i32 s40, s20, s37
	s_cmp_ge_u32 s20, s37
	s_cselect_b32 s21, s36, s21
	s_cselect_b32 s20, s40, s20
	s_add_i32 s36, s21, 1
	s_cmp_ge_u32 s20, s37
	s_cselect_b32 s20, s36, s21
	s_xor_b32 s20, s20, s13
	s_sub_i32 s13, s20, s13
	s_lshl_b32 s20, s13, 2
	s_sub_i32 s10, s10, s20
	s_min_i32 s21, s10, 4
	s_abs_i32 s10, s21
	v_cvt_f32_u32_e32 v1, s10
	v_and_b32_e32 v2, 0x7fffc0, v4
	v_and_b32_e32 v3, 60, v3
	v_bfe_u32 v4, v4, 4, 2
	v_or3_b32 v2, v2, v3, v4
	v_lshl_add_u32 v216, v2, 9, v0
	v_rcp_iflag_f32_e32 v0, v1
	s_sub_i32 s36, 0, s10
	s_mul_i32 s13, s13, s12
	s_sub_i32 s12, s11, s13
	v_mul_f32_e32 v0, 0x4f7ffffe, v0
	v_cvt_u32_f32_e32 v0, v0
	s_abs_i32 s13, s12
	s_xor_b32 s11, s12, s21
	s_ashr_i32 s11, s11, 31
	v_readfirstlane_b32 s37, v0
	s_mul_i32 s36, s36, s37
	s_mul_hi_u32 s36, s37, s36
	s_add_i32 s37, s37, s36
	s_mul_hi_u32 s36, s13, s37
	s_mul_i32 s37, s36, s10
	s_sub_i32 s13, s13, s37
	s_add_i32 s37, s36, 1
	s_sub_i32 s40, s13, s10
	s_cmp_ge_u32 s13, s10
	s_cselect_b32 s36, s37, s36
	s_cselect_b32 s13, s40, s13
	s_add_i32 s37, s36, 1
	s_cmp_ge_u32 s13, s10
	s_cselect_b32 s10, s37, s36
	s_xor_b32 s10, s10, s11
	s_sub_i32 s10, s10, s11
	s_mul_i32 s13, s10, s21
	s_sub_i32 s12, s12, s13
	s_add_i32 s12, s12, s20
	s_ashr_i32 s53, s52, 31
	s_ashr_i32 s11, s10, 31
	s_ashr_i32 s13, s12, 31
	s_ashr_i32 s51, s50, 31
	s_lshl_b64 s[20:21], s[52:53], 17
	s_add_u32 s40, s8, s20
	s_addc_u32 s41, s9, s21
	s_lshl_b64 s[36:37], s[50:51], 20
	s_add_u32 s36, s56, s36
	s_addc_u32 s37, s57, s37
	s_add_u32 s20, s36, s20
	s_addc_u32 s21, s37, s21
	s_lshl_b64 s[10:11], s[10:11], 17
	s_add_u32 s76, s20, s10
	s_addc_u32 s77, s21, s11
	s_add_i32 s51, s29, 0
	s_add_i32 m0, s51, 0x10000
	v_mov_b32_e32 v215, v193
	global_load_lds_dwordx4 v214, s[76:77]
	s_add_i32 m0, s51, 0x12000
	s_add_u32 s10, s76, 0x10000
	global_load_lds_dwordx4 v210, s[76:77]
	s_addc_u32 s11, s77, 0
	s_add_i32 m0, s51, 0x14000
	v_mov_b32_e32 v211, v193
	global_load_lds_dwordx4 v214, s[10:11]
	s_add_i32 m0, s51, 0x16000
	v_mov_b32_e32 v217, v193
	global_load_lds_dwordx4 v210, s[10:11]
	s_lshl_b64 s[10:11], s[12:13], 17
	s_add_u32 s60, s40, s10
	s_addc_u32 s61, s41, s11
	s_add_i32 s53, s51, 0x2000
	s_mov_b32 m0, s51
	s_add_u32 s10, s60, 0x10000
	global_load_lds_dwordx4 v216, s[60:61]
	s_mov_b32 m0, s53
	s_addc_u32 s11, s61, 0
	s_add_i32 s62, s51, 0x4000
	global_load_lds_dwordx4 v212, s[60:61]
	s_mov_b32 m0, s62
	s_add_i32 s68, s51, 0x6000
	global_load_lds_dwordx4 v216, s[10:11]
	s_mov_b32 m0, s68
	v_mov_b32_e32 v213, v193
	global_load_lds_dwordx4 v212, s[10:11]
	s_load_dwordx2 s[10:11], s[30:31], 0x60
	v_lshl_add_u64 v[6:7], s[76:77], 0, v[214:215]
	v_lshl_add_u64 v[4:5], s[76:77], 0, v[210:211]
	v_lshl_add_u64 v[2:3], s[60:61], 0, v[216:217]
	s_and_b64 vcc, exec, s[38:39]
	v_lshl_add_u64 v[0:1], s[60:61], 0, v[212:213]
	s_cbranch_vccnz .LBB0_501
	s_barrier

;     __device__ __forceinline__ bool next(int i, Unit& u) const {
;         int nM = this->nM, nN = this->nN, Z2 = this->Z2; asm volatile("" : "+s"(nM), "+s"(nN), "+s"(Z2));
;         const long L = (long)i * G + c; if (L >= nwg) return false;
;         int wgid = (int)L; { const int q = nwg / NXCD, r = nwg % NXCD, xcd = wgid % NXCD, off = wgid / NXCD; wgid = (xcd < r ? xcd * (q + 1) : r * (q + 1) + (xcd - r) * q) + off; }
;         if (rev) wgid = nwg - 1 - wgid;
;         const int per = nM * nN, z = wgid / per, rem = wgid - z * per;
;         const int nig = WGM * nN, gid = rem / nig, fm = gid * WGM, gsz = (nM - fm) < WGM ? (nM - fm) : WGM, ri = rem - gid * nig;
;         u.pm = fm + (ri % gsz); u.pn = ri / gsz; u.z1 = z / Z2; u.z2 = z - u.z1 * Z2; return true;
.LBB0_504:
	v_cmp_gt_i64_e32 vcc, s[20:21], v[202:203]
	s_mov_b32 s10, 8
	s_mov_b32 s11, 1
	s_mov_b32 s12, 1
	v_cmp_lt_i64_e64 s[48:49], s[20:21], v[200:201]
	s_cbranch_vccnz .LBB0_506
	s_ashr_i32 s13, s20, 31
	s_lshr_b32 s13, s13, 29
	s_add_i32 s13, s20, s13
	s_ashr_i32 s30, s13, 3
	s_and_b32 s13, s13, -8
	s_sub_i32 s13, s20, s13
	s_cmp_lt_i32 s13, 0
	s_movk_i32 s4, 0xa1
	s_mul_i32 s36, s11, s12
	s_cselect_b32 s31, s4, 0xa0
	s_abs_i32 s37, s36
	s_mul_i32 s13, s13, s31
	s_sub_i32 s31, 0, s37
	s_add_i32 s13, s13, s30
	s_abs_i32 s40, s13
	s_xor_b32 s30, s13, s36
	s_ashr_i32 s30, s30, 31
	s_mov_b32 s41, 0xffffffff
	s_mul_i32 s31, s31, s41
	s_mul_hi_u32 s31, s41, s31
	s_add_i32 s41, s41, s31
	s_mul_hi_u32 s31, s40, s41
	s_mul_i32 s41, s31, s37
	s_sub_i32 s40, s40, s41
	s_add_i32 s41, s31, 1
	s_sub_i32 s42, s40, s37
	s_cmp_ge_u32 s40, s37
	s_cselect_b32 s31, s41, s31
	s_cselect_b32 s40, s42, s40
	s_add_i32 s41, s31, 1
	s_cmp_ge_u32 s40, s37
	s_cselect_b32 s31, s41, s31
	s_lshl_b32 s12, s12, 2
	s_abs_i32 s37, s12
	s_xor_b32 s31, s31, s30
	s_sub_i32 s31, s31, s30
	s_sub_i32 s40, 0, s37
	s_mul_i32 s30, s31, s36
	s_sub_i32 s13, s13, s30
	s_abs_i32 s36, s13
	s_xor_b32 s30, s13, s12
	s_ashr_i32 s30, s30, 31
	s_mov_b32 s41, 0x40000000
	s_mul_i32 s40, s40, s41
	s_mul_hi_u32 s40, s41, s40
	s_add_i32 s41, s41, s40
	s_mul_hi_u32 s40, s36, s41
	s_mul_i32 s41, s40, s37
	s_sub_i32 s36, s36, s41
	s_add_i32 s41, s40, 1
	s_sub_i32 s42, s36, s37
	s_cmp_ge_u32 s36, s37
	s_cselect_b32 s40, s41, s40
	s_cselect_b32 s36, s42, s36
	s_add_i32 s41, s40, 1
	s_cmp_ge_u32 s36, s37
	s_cselect_b32 s36, s41, s40
	s_xor_b32 s36, s36, s30
	s_sub_i32 s30, s36, s30
	s_lshl_b32 s36, s30, 2
	s_sub_i32 s11, s11, s36
	s_min_i32 s11, s11, 4
	s_abs_i32 s37, s11
	v_cvt_f32_u32_e32 v0, s37
	s_sub_i32 s40, 0, s37
	s_mul_i32 s30, s30, s12
	s_sub_i32 s12, s13, s30
	v_rcp_iflag_f32_e32 v0, v0
	s_abs_i32 s30, s12
	s_xor_b32 s13, s12, s11
	s_ashr_i32 s13, s13, 31
	v_mul_f32_e32 v0, 0x4f7ffffe, v0
	v_cvt_u32_f32_e32 v0, v0
	s_nop 0
	v_readfirstlane_b32 s41, v0
	s_mul_i32 s40, s40, s41
	s_mul_hi_u32 s40, s41, s40
	s_add_i32 s41, s41, s40
	s_mul_hi_u32 s40, s30, s41
	s_mul_i32 s41, s40, s37
	s_sub_i32 s30, s30, s41
	s_add_i32 s41, s40, 1
	s_sub_i32 s42, s30, s37
	s_cmp_ge_u32 s30, s37
	s_cselect_b32 s40, s41, s40
	s_cselect_b32 s30, s42, s30
	s_add_i32 s41, s40, 1
	s_cmp_ge_u32 s30, s37
	s_cselect_b32 s30, s41, s40
	s_abs_i32 s37, s10
	s_xor_b32 s30, s30, s13
	s_sub_i32 s30, s30, s13
	s_sub_i32 s13, 0, s37
	s_mul_i32 s11, s30, s11
	s_sub_i32 s11, s12, s11
	s_abs_i32 s12, s31
	s_add_i32 s36, s36, s11
	s_xor_b32 s11, s31, s10
	s_ashr_i32 s11, s11, 31
	s_mov_b32 s40, 0x20000000
	s_mul_i32 s13, s13, s40
	s_mul_hi_u32 s13, s40, s13
	s_add_i32 s40, s40, s13
	s_mul_hi_u32 s13, s12, s40
	s_mul_i32 s40, s13, s37
	s_sub_i32 s12, s12, s40
	s_add_i32 s40, s13, 1
	s_sub_i32 s41, s12, s37
	s_cmp_ge_u32 s12, s37
	s_cselect_b32 s13, s40, s13
	s_cselect_b32 s12, s41, s12
	s_add_i32 s40, s13, 1
	s_cmp_ge_u32 s12, s37
	s_cselect_b32 s12, s40, s13
	s_xor_b32 s12, s12, s11
	s_sub_i32 s40, s12, s11
	s_mul_i32 s10, s40, s10
	s_sub_i32 s42, s31, s10

;     __device__ __forceinline__ bool next(int i, Unit& u) const {
;         int nM = this->nM, nN = this->nN, Z2 = this->Z2; asm volatile("" : "+s"(nM), "+s"(nN), "+s"(Z2));
;         const long L = (long)i * G + c; if (L >= nwg) return false;
;         int wgid = (int)L; { const int q = nwg / NXCD, r = nwg % NXCD, xcd = wgid % NXCD, off = wgid / NXCD; wgid = (xcd < r ? xcd * (q + 1) : r * (q + 1) + (xcd - r) * q) + off; }
;         if (rev) wgid = nwg - 1 - wgid;
;         const int per = nM * nN, z = wgid / per, rem = wgid - z * per;
;         const int nig = WGM * nN, gid = rem / nig, fm = gid * WGM, gsz = (nM - fm) < WGM ? (nM - fm) : WGM, ri = rem - gid * nig;
;         u.pm = fm + (ri % gsz); u.pn = ri / gsz; u.z1 = z / Z2; u.z2 = z - u.z1 * Z2; return true;
.LBB0_516:
	v_readlane_b32 s4, v254, 36
	v_readlane_b32 s5, v254, 37
	s_mov_b32 s10, 1
	s_movk_i32 s8, 0xa0
	v_cndmask_b32_e64 v0, 0, 1, s[4:5]
	s_mov_b32 s9, 16
	v_cmp_ne_u32_e64 s[46:47], 1, v0
	s_andn2_b64 vcc, exec, s[4:5]
	v_mbcnt_lo_u32_b32 v8, -1, 0
	v_mbcnt_hi_u32_b32 v8, -1, v8
	s_cbranch_vccnz .LBB0_518
	s_mul_i32 s10, s8, s9
	s_abs_i32 s10, s10
	s_sub_i32 s11, 0, s10
	v_readlane_b32 s4, v254, 51
	s_nop 0
	s_mov_b32 s12, 0x199999
	s_mul_i32 s11, s11, s12
	s_mul_hi_u32 s11, s12, s11
	s_add_i32 s12, s12, s11
	s_mul_hi_u32 s11, s4, s12
	s_mul_i32 s11, s11, s10
	s_sub_i32 s11, s4, s11
	s_sub_i32 s12, s11, s10
	s_cmp_ge_u32 s11, s10
	s_cselect_b32 s11, s12, s11
	s_sub_i32 s12, s11, s10
	s_cmp_ge_u32 s11, s10
	s_cselect_b32 s10, s12, s11
	s_lshl_b32 s9, s9, 2
	s_abs_i32 s11, s9
	v_readlane_b32 s4, v254, 50
	s_sub_i32 s12, 0, s11
	s_xor_b32 s10, s10, s4
	s_sub_i32 s10, s10, s4
	s_abs_i32 s20, s10
	s_xor_b32 s13, s10, s9
	s_ashr_i32 s13, s13, 31
	s_mov_b32 s21, 0x4000000
	s_mul_i32 s12, s12, s21
	s_mul_hi_u32 s12, s21, s12
	s_add_i32 s21, s21, s12
	s_mul_hi_u32 s12, s20, s21
	s_mul_i32 s21, s12, s11
	s_sub_i32 s20, s20, s21
	s_add_i32 s30, s12, 1
	s_sub_i32 s21, s20, s11
	s_cmp_ge_u32 s20, s11
	s_cselect_b32 s12, s30, s12
	s_cselect_b32 s20, s21, s20
	s_add_i32 s21, s12, 1
	s_cmp_ge_u32 s20, s11
	s_cselect_b32 s11, s21, s12
	s_xor_b32 s11, s11, s13
	s_sub_i32 s11, s11, s13
	s_lshl_b32 s12, s11, 2
	s_sub_i32 s8, s8, s12
	s_min_i32 s8, s8, 4
	s_abs_i32 s13, s8
	v_cvt_f32_u32_e32 v0, s13
	s_sub_i32 s20, 0, s13
	s_mul_i32 s11, s11, s9
	s_sub_i32 s9, s10, s11
	v_rcp_iflag_f32_e32 v0, v0
	s_abs_i32 s10, s9
	s_xor_b32 s11, s9, s8
	s_ashr_i32 s11, s11, 31
	v_mul_f32_e32 v0, 0x4f7ffffe, v0
	v_cvt_u32_f32_e32 v0, v0
	s_nop 0
	v_readfirstlane_b32 s21, v0
	s_mul_i32 s20, s20, s21
	s_mul_hi_u32 s20, s21, s20
	s_add_i32 s21, s21, s20
	s_mul_hi_u32 s20, s10, s21
	s_mul_i32 s21, s20, s13
	s_sub_i32 s10, s10, s21
	s_add_i32 s30, s20, 1
	s_sub_i32 s21, s10, s13
	s_cmp_ge_u32 s10, s13
	s_cselect_b32 s20, s30, s20
	s_cselect_b32 s10, s21, s10
	s_add_i32 s21, s20, 1
	s_cmp_ge_u32 s10, s13
	s_cselect_b32 s10, s21, s20
	s_xor_b32 s10, s10, s11
	s_sub_i32 s44, s10, s11
	s_mul_i32 s8, s44, s8
	s_sub_i32 s8, s9, s8
	s_add_i32 s40, s12, s8

;     __device__ __forceinline__ bool next(int i, Unit& u) const {
;         int nM = this->nM, nN = this->nN, Z2 = this->Z2; asm volatile("" : "+s"(nM), "+s"(nN), "+s"(Z2));
;         const long L = (long)i * G + c; if (L >= nwg) return false;
;         int wgid = (int)L; { const int q = nwg / NXCD, r = nwg % NXCD, xcd = wgid % NXCD, off = wgid / NXCD; wgid = (xcd < r ? xcd * (q + 1) : r * (q + 1) + (xcd - r) * q) + off; }
;         if (rev) wgid = nwg - 1 - wgid;
;         const int per = nM * nN, z = wgid / per, rem = wgid - z * per;
;         const int nig = WGM * nN, gid = rem / nig, fm = gid * WGM, gsz = (nM - fm) < WGM ? (nM - fm) : WGM, ri = rem - gid * nig;
;         u.pm = fm + (ri % gsz); u.pn = ri / gsz; u.z1 = z / Z2; u.z2 = z - u.z1 * Z2; return true;
.LBB0_524:
	s_mov_b32 s10, 1
	s_movk_i32 s8, 0xa0
	s_mov_b32 s9, 16
	s_add_i32 s95, s95, 1
	s_mul_i32 s10, s95, s94
	s_mul_hi_u32 s11, s95, s87
	s_add_i32 s11, s11, s10
	s_mul_i32 s10, s95, s87
	s_add_u32 s10, s10, s2
	s_addc_u32 s11, s11, s33
	v_mov_b64_e32 v[0:1], 0xa00
	v_cmp_lt_i64_e64 s[46:47], s[10:11], v[0:1]
	v_mov_b64_e32 v[0:1], 0x9ff
	v_cmp_gt_i64_e64 s[48:49], s[10:11], v[0:1]
	s_and_b64 vcc, exec, s[48:49]
	s_cbranch_vccnz .LBB0_526
	s_ashr_i32 s11, s10, 31
	s_lshr_b32 s11, s11, 29
	s_add_i32 s11, s10, s11
	s_ashr_i32 s30, s11, 3
	s_and_b32 s11, s11, -8
	s_sub_i32 s10, s10, s11
	s_cmp_lt_i32 s10, 0
	s_mul_i32 s31, s8, s9
	s_cselect_b32 s11, s4, 0x140
	s_abs_i32 s31, s31
	s_mul_i32 s10, s10, s11
	s_sub_i32 s11, 0, s31
	s_add_i32 s10, s10, s30
	s_ashr_i32 s30, s10, 31
	s_abs_i32 s10, s10
	s_mov_b32 s36, 0x199999
	s_mul_i32 s11, s11, s36
	s_mul_hi_u32 s11, s36, s11
	s_add_i32 s36, s36, s11
	s_mul_hi_u32 s11, s10, s36
	s_mul_i32 s11, s11, s31
	s_sub_i32 s10, s10, s11
	s_sub_i32 s11, s10, s31
	s_cmp_ge_u32 s10, s31
	s_cselect_b32 s10, s11, s10
	s_sub_i32 s11, s10, s31
	s_cmp_ge_u32 s10, s31
	s_cselect_b32 s10, s11, s10
	s_lshl_b32 s9, s9, 2
	s_abs_i32 s11, s9
	s_xor_b32 s10, s10, s30
	s_sub_i32 s10, s10, s30
	s_sub_i32 s30, 0, s11
	s_abs_i32 s36, s10
	s_xor_b32 s31, s10, s9
	s_ashr_i32 s31, s31, 31
	s_mov_b32 s37, 0x4000000
	s_mul_i32 s30, s30, s37
	s_mul_hi_u32 s30, s37, s30
	s_add_i32 s37, s37, s30
	s_mul_hi_u32 s30, s36, s37
	s_mul_i32 s37, s30, s11
	s_sub_i32 s36, s36, s37
	s_add_i32 s42, s30, 1
	s_sub_i32 s37, s36, s11
	s_cmp_ge_u32 s36, s11
	s_cselect_b32 s30, s42, s30
	s_cselect_b32 s36, s37, s36
	s_add_i32 s37, s30, 1
	s_cmp_ge_u32 s36, s11
	s_cselect_b32 s11, s37, s30
	s_xor_b32 s11, s11, s31
	s_sub_i32 s11, s11, s31
	s_lshl_b32 s30, s11, 2
	s_sub_i32 s8, s8, s30
	s_min_i32 s8, s8, 4
	s_abs_i32 s31, s8
	v_cvt_f32_u32_e32 v0, s31
	s_sub_i32 s36, 0, s31
	s_mul_i32 s11, s11, s9
	s_sub_i32 s9, s10, s11
	v_rcp_iflag_f32_e32 v0, v0
	s_abs_i32 s10, s9
	s_xor_b32 s11, s9, s8
	s_ashr_i32 s11, s11, 31
	v_mul_f32_e32 v0, 0x4f7ffffe, v0
	v_cvt_u32_f32_e32 v0, v0
	s_nop 0
	v_readfirstlane_b32 s37, v0
	s_mul_i32 s36, s36, s37
	s_mul_hi_u32 s36, s37, s36
	s_add_i32 s37, s37, s36
	s_mul_hi_u32 s36, s10, s37
	s_mul_i32 s37, s36, s31
	s_sub_i32 s10, s10, s37
	s_add_i32 s42, s36, 1
	s_sub_i32 s37, s10, s31
	s_cmp_ge_u32 s10, s31
	s_cselect_b32 s36, s42, s36
	s_cselect_b32 s10, s37, s10
	s_add_i32 s37, s36, 1
	s_cmp_ge_u32 s10, s31
	s_cselect_b32 s10, s37, s36
	s_xor_b32 s10, s10, s11
	s_sub_i32 s58, s10, s11
	s_mul_i32 s8, s58, s8
	s_sub_i32 s8, s9, s8
	s_add_i32 s36, s30, s8

; #define PG8_BAR __builtin_amdgcn_s_barrier()
;     __device__ __forceinline__ bool next(int i, Unit& u) const {
;         int nM = this->nM, nN = this->nN, Z2 = this->Z2; asm volatile("" : "+s"(nM), "+s"(nN), "+s"(Z2));
; template <class Epi>
; __device__ __forceinline__ void gemm_phase(PG8_LAS unsigned char* lds, PG8_LAS unsigned char* xl, const Gemm g, const Sched& S, const Epi& E, const int wid) {
;     const int lane = lane_id_opq(), tid = wid * 64 + lane;
;     const int wr = wid >> 2, wc = wid & 3, fr = lane & 15, fq = lane >> 4;
;     const int K = g.K, nt = K / BK;
;     unsigned voffA[2], voffB[2];
; #pragma unroll
;     for (int i = 0; i < 2; ++i) { int R, C; stage_rc(tid * 16 + i * 8192, R, C); const int Rb = Epi::PERM ? ((R & ~31) + perm32(R & 31)) : R;
;         const int Ra = Epi::PERM ? ((R & ~63) + 4 * (R & 15) + ((R >> 4) & 3)) : R;
;         voffA[i] = (unsigned)(Ra * g.lda + C) * 2u; voffB[i] = (unsigned)(Rb * g.ldb + C) * 2u; }
;     const size_t kstep = (size_t)(BK * 2);
;     const size_t hstepA = (size_t)HALF * g.lda * 2, hstepB = (size_t)HALF * g.ldb * 2;
;     const unsigned ldsw = (unsigned)wid * 1024u;
;     const int aoff = lds_byte(wr * 64 + fr, fq * 8), boff = lds_byte(wc * 32 + fr, fq * 8);
;     ...
;     Unit cur, nxt; int ui = 0;
;     if (!S.next(0, cur)) return;
;     Acc acc;
; #pragma unroll
;     for (int a = 0; a < 2; ++a)
; #pragma unroll
;         for (int b = 0; b < 2; ++b)
; #pragma unroll
;             for (int m = 0; m < 4; ++m)
; #pragma unroll
;                 for (int n = 0; n < 2; ++n) acc[a][b][m][n] = (f32x4){0.f, 0.f, 0.f, 0.f};
;     bf16x8 At[4][2], B0[2][2], B1[2][2];
;     float prc[8];
; #pragma unroll
;     for (int k = 0; k < 8; ++k) prc[k] = 1.0f;
;     if constexpr (Epi::PRE) { const float* pb = E.pre_base(cur) + wr * 64 + 4 * fr;
; #pragma unroll
;         for (int k = 0; k < 8; ++k) prc[k] = pb[(k >> 2) * HALF + (k & 3)]; }
;     const char* cA = a_tile(g, cur); const char* cB = b_tile(g, cur);
;     PG8_STAGE(PG8_SB(0, 0), cB, voffB); PG8_STAGE(PG8_SB(0, 1), cB + hstepB, voffB); PG8_STAGE(PG8_SA(0, 0), cA, voffA); PG8_STAGE(PG8_SA(0, 1), cA + hstepA, voffA);
;     if (wr == 1) PG8_BAR;
;     PG8_WAIT_V(2); PG8_BAR;
;     PG8_STAGE(PG8_SB(1, 0), cB + kstep, voffB); PG8_STAGE(PG8_SA(1, 0), cA + kstep, voffA); PG8_STAGE(PG8_SB(1, 1), cB + hstepB + kstep, voffB);
;     PG8_WAIT_V(6); PG8_BAR;
.LBB0_678:
	v_readlane_b32 s4, v252, 46
	v_readlane_b32 s8, v253, 0
	v_readlane_b32 s5, v252, 47
	v_readlane_b32 s9, v253, 1
	v_readlane_b32 s0, v252, 41
	s_mov_b32 s11, 8
	s_mov_b32 s1, 1
	s_movk_i32 s10, 0xa0
	s_and_b64 vcc, exec, s[4:5]
	s_waitcnt lgkmcnt(0)
	s_barrier
	v_mbcnt_lo_u32_b32 v15, -1, 0
	v_mbcnt_hi_u32_b32 v15, -1, v15
	s_cbranch_vccnz .LBB0_698
	v_lshlrev_b32_e32 v17, 4, v15
	v_add_u32_e32 v0, s29, v17
	v_add_u32_e32 v1, 0x2000, v0
	v_ashrrev_i32_e32 v2, 31, v1
	v_lshrrev_b32_e32 v2, 22, v2
	v_add_u32_e32 v2, v1, v2
	v_ashrrev_i32_e32 v2, 10, v2
	v_mul_i32_i24_e32 v3, 0x400, v2
	v_sub_u32_e32 v1, v1, v3
	v_lshrrev_b32_e32 v3, 4, v1
	v_bitop3_b32 v1, v3, v1, 32 bitop3:0x6c
	v_ashrrev_i32_e32 v3, 31, v1
	v_lshrrev_b32_e32 v3, 26, v3
	v_add_u32_e32 v3, v1, v3
	v_lshlrev_b32_e32 v5, 3, v2
	v_lshlrev_b32_e32 v2, 5, v2
	v_and_b32_e32 v8, 32, v2
	v_and_b32_e32 v2, 0xffc0, v3
	v_sub_u32_e32 v1, v1, v2
	v_lshrrev_b16_e32 v2, 7, v1
	v_and_b32_e32 v2, 1, v2
	v_ashrrev_i32_e32 v4, 6, v3
	v_and_b32_e32 v5, -16, v5
	v_add_u16_e32 v1, v1, v2
	v_add_u32_e32 v5, v4, v5
	v_ashrrev_i16_sdwa v1, v244, sext(v1) dst_sel:DWORD dst_unused:UNUSED_PAD src0_sel:DWORD src1_sel:BYTE_0
	v_and_b32_e32 v4, 3, v4
	s_mov_b32 s4, 0xfffe0
	v_lshrrev_b32_e32 v6, 2, v5
	v_lshlrev_b32_e32 v7, 1, v5
	v_bfe_i32 v9, v1, 0, 16
	v_and_or_b32 v4, v5, s4, v4
	v_and_b32_e32 v6, 4, v6
	v_and_b32_e32 v7, 24, v7
	v_add_u32_e32 v1, v8, v9
	v_or3_b32 v4, v4, v6, v7
	v_lshlrev_b32_e32 v2, 1, v1
	s_load_dwordx2 s[12:13], s[8:9], 0xd8
	v_lshl_add_u32 v152, v4, 12, v2
	v_lshlrev_b32_e32 v2, 2, v5
	v_and_b32_e32 v10, 0x7fffffc0, v5
	v_and_b32_e32 v11, 60, v2
	v_bfe_u32 v12, v5, 4, 2
	v_or3_b32 v2, v10, v11, v12
	v_mul_lo_u32 v2, v2, s17
	v_add_lshl_u32 v154, v2, v1, 1
	v_ashrrev_i32_e32 v1, 31, v0
	s_waitcnt lgkmcnt(0)
	s_add_u32 s1, s12, 0x27800000
	v_lshrrev_b32_e32 v1, 22, v1
	s_addc_u32 s8, s13, 0
	v_add_u32_e32 v1, v0, v1
	s_add_u32 s9, s12, 0x3000000
	v_ashrrev_i32_e32 v1, 10, v1
	s_mul_i32 s20, s10, s11
	s_addc_u32 s52, s13, 0
	v_mul_i32_i24_e32 v2, 0x400, v1
	v_lshlrev_b32_e32 v4, 3, v1
	v_lshlrev_b32_e32 v1, 5, v1
	s_abs_i32 s20, s20
	v_and_b32_e32 v13, 32, v1
	v_sub_u32_e32 v0, v0, v2
	v_lshrrev_b32_e32 v2, 4, v0
	v_bitop3_b32 v0, v2, v0, 32 bitop3:0x6c
	v_ashrrev_i32_e32 v2, 31, v0
	v_lshrrev_b32_e32 v2, 26, v2
	v_add_u32_e32 v2, v0, v2
	s_sub_i32 s21, 0, s20
	v_ashrrev_i32_e32 v3, 6, v2
	v_and_b32_e32 v4, -16, v4
	s_mov_b32 s30, 0x333333
	s_mul_i32 s21, s21, s30
	v_add_u32_e32 v4, v3, v4
	v_and_b32_e32 v3, 3, v3
	s_mul_hi_u32 s21, s30, s21
	v_and_or_b32 v3, v4, s4, v3
	s_add_i32 s30, s30, s21
	v_readlane_b32 s4, v254, 53
	s_mul_hi_u32 s21, s4, s30
	s_mul_i32 s21, s21, s20
	s_sub_i32 s21, s4, s21
	s_sub_i32 s30, s21, s20
	s_cmp_ge_u32 s21, s20
	s_cselect_b32 s21, s30, s21
	s_sub_i32 s30, s21, s20
	s_cmp_ge_u32 s21, s20
	s_cselect_b32 s20, s30, s21
	s_lshl_b32 s11, s11, 2
	s_abs_i32 s21, s11
	v_readlane_b32 s4, v254, 52
	s_sub_i32 s36, 0, s21
	s_xor_b32 s20, s20, s4
	s_sub_i32 s20, s20, s4
	s_abs_i32 s31, s20
	s_xor_b32 s30, s20, s11
	s_ashr_i32 s30, s30, 31
	v_and_b32_e32 v2, 0xc0, v2
	v_sub_u32_e32 v0, v0, v2
	s_mov_b32 s37, 0x8000000
	s_mul_i32 s36, s36, s37
	s_mul_hi_u32 s36, s37, s36
	s_add_i32 s37, s37, s36
	s_mul_hi_u32 s36, s31, s37
	s_mul_i32 s37, s36, s21
	s_sub_i32 s31, s31, s37
	s_add_i32 s37, s36, 1
	s_sub_i32 s40, s31, s21
	s_cmp_ge_u32 s31, s21
	s_cselect_b32 s36, s37, s36
	s_cselect_b32 s31, s40, s31
	s_add_i32 s37, s36, 1
	s_cmp_ge_u32 s31, s21
	s_cselect_b32 s21, s37, s36
	s_xor_b32 s21, s21, s30
	s_sub_i32 s21, s21, s30
	v_ashrrev_i16_sdwa v0, v244, sext(v0) dst_sel:DWORD dst_unused:UNUSED_PAD src0_sel:DWORD src1_sel:BYTE_0
	s_lshl_b32 s30, s21, 2
	v_lshrrev_b32_e32 v5, 2, v4
	v_lshlrev_b32_e32 v6, 1, v4
	v_bfe_i32 v14, v0, 0, 16
	s_sub_i32 s10, s10, s30
	v_and_b32_e32 v5, 4, v5
	v_and_b32_e32 v6, 24, v6
	v_add_u32_e32 v0, v13, v14
	s_min_i32 s10, s10, 4
	v_or3_b32 v3, v3, v5, v6
	v_lshlrev_b32_e32 v2, 1, v0
	s_abs_i32 s31, s10
	v_lshl_add_u32 v156, v3, 12, v2
	v_lshlrev_b32_e32 v2, 2, v4
	v_cvt_f32_u32_e32 v1, s31
	v_and_b32_e32 v16, 0x7fffffc0, v4
	v_and_b32_e32 v18, 60, v2
	v_bfe_u32 v19, v4, 4, 2
	v_or3_b32 v2, v16, v18, v19
	v_mul_lo_u32 v2, v2, s17
	v_add_lshl_u32 v158, v2, v0, 1
	v_rcp_iflag_f32_e32 v0, v1
	s_sub_i32 s36, 0, s31
	s_mul_i32 s21, s21, s11
	s_sub_i32 s11, s20, s21
	v_mul_f32_e32 v0, 0x4f7ffffe, v0
	v_cvt_u32_f32_e32 v0, v0
	s_abs_i32 s21, s11
	s_xor_b32 s20, s11, s10
	s_ashr_i32 s20, s20, 31
	v_readfirstlane_b32 s37, v0
	s_mul_i32 s36, s36, s37
	s_mul_hi_u32 s36, s37, s36
	s_add_i32 s37, s37, s36
	s_mul_hi_u32 s36, s21, s37
	s_mul_i32 s37, s36, s31
	s_sub_i32 s21, s21, s37
	s_add_i32 s37, s36, 1
	s_sub_i32 s40, s21, s31
	s_cmp_ge_u32 s21, s31
	s_cselect_b32 s36, s37, s36
	s_cselect_b32 s21, s40, s21
	s_add_i32 s37, s36, 1
	s_cmp_ge_u32 s21, s31
	s_cselect_b32 s21, s37, s36
	s_xor_b32 s21, s21, s20
	s_sub_i32 s40, s21, s20
	s_mul_i32 s10, s40, s10
	s_sub_i32 s10, s11, s10
	s_ashr_i32 s41, s40, 31
	s_add_i32 s66, s30, s10
	s_lshl_b64 s[10:11], s[40:41], 20
	s_add_u32 s44, s9, s10
	s_addc_u32 s45, s52, s11
	s_add_i32 s53, s29, 0
	s_add_i32 m0, s53, 0x10000
	v_mov_b32_e32 v157, v193
	global_load_lds_dwordx4 v156, s[44:45]
	s_add_i32 m0, s53, 0x12000
	s_add_u32 s10, s44, 0x80000
	global_load_lds_dwordx4 v152, s[44:45]
	s_addc_u32 s11, s45, 0
	s_add_i32 m0, s53, 0x14000
	v_mov_b32_e32 v153, v193
	global_load_lds_dwordx4 v156, s[10:11]
	s_add_i32 m0, s53, 0x16000
	v_mov_b32_e32 v159, v193
	global_load_lds_dwordx4 v152, s[10:11]
	s_mul_i32 s11, s66, 0x580000
	s_mul_hi_i32 s10, s66, 0x580000
	s_add_u32 s36, s1, s11
	s_addc_u32 s37, s8, s10
	s_add_i32 s56, s53, 0x2000
	s_mov_b32 m0, s53
	s_add_u32 s10, s36, 0x2c0000
	global_load_lds_dwordx4 v158, s[36:37]
	s_mov_b32 m0, s56
	s_addc_u32 s11, s37, 0
	s_add_i32 s57, s53, 0x4000
	global_load_lds_dwordx4 v154, s[36:37]
	s_mov_b32 m0, s57
	s_add_i32 s58, s53, 0x6000
	global_load_lds_dwordx4 v158, s[10:11]
	s_mov_b32 m0, s58
	v_mov_b32_e32 v155, v193
	global_load_lds_dwordx4 v154, s[10:11]
	v_lshl_add_u64 v[6:7], s[44:45], 0, v[156:157]
	v_lshl_add_u64 v[4:5], s[44:45], 0, v[152:153]
	v_lshl_add_u64 v[2:3], s[36:37], 0, v[158:159]
	s_and_b64 vcc, exec, s[38:39]
	v_lshl_add_u64 v[0:1], s[36:37], 0, v[154:155]
	s_cbranch_vccnz .LBB0_681
	s_barrier

;     __device__ __forceinline__ bool next(int i, Unit& u) const {
;         int nM = this->nM, nN = this->nN, Z2 = this->Z2; asm volatile("" : "+s"(nM), "+s"(nN), "+s"(Z2));
;         const long L = (long)i * G + c; if (L >= nwg) return false;
;         int wgid = (int)L; { const int q = nwg / NXCD, r = nwg % NXCD, xcd = wgid % NXCD, off = wgid / NXCD; wgid = (xcd < r ? xcd * (q + 1) : r * (q + 1) + (xcd - r) * q) + off; }
;         if (rev) wgid = nwg - 1 - wgid;
;         const int per = nM * nN, z = wgid / per, rem = wgid - z * per;
;         const int nig = WGM * nN, gid = rem / nig, fm = gid * WGM, gsz = (nM - fm) < WGM ? (nM - fm) : WGM, ri = rem - gid * nig;
;         u.pm = fm + (ri % gsz); u.pn = ri / gsz; u.z1 = z / Z2; u.z2 = z - u.z1 * Z2; return true;
.LBB0_684:
	s_mov_b32 s20, 8
	s_mov_b32 s10, 1
	s_movk_i32 s13, 0xa0
	s_add_i32 s88, s88, 1
	s_mul_i32 s10, s88, s87
	s_mul_hi_u32 s11, s88, s0
	s_add_i32 s11, s11, s10
	s_mul_i32 s10, s88, s0
	s_add_u32 s10, s10, s2
	s_addc_u32 s11, s11, s33
	v_cmp_gt_i64_e32 vcc, s[10:11], v[202:203]
	v_cmp_lt_i64_e64 s[48:49], s[10:11], v[200:201]
	s_cbranch_vccnz .LBB0_686
	s_ashr_i32 s11, s10, 31
	s_lshr_b32 s11, s11, 29
	s_add_i32 s11, s10, s11
	s_and_b32 s12, s11, -8
	s_sub_i32 s10, s10, s12
	s_ashr_i32 s11, s11, 3
	s_cmp_lt_i32 s10, 0
	s_mul_i32 s21, s13, s20
	s_cselect_b32 s12, s4, 0xffffff60
	s_abs_i32 s21, s21
	s_mul_i32 s10, s10, s12
	s_sub_i32 s12, 0, s21
	s_sub_i32 s10, s10, s11
	s_addk_i32 s10, 0x4ff
	s_ashr_i32 s11, s10, 31
	s_abs_i32 s10, s10
	s_mov_b32 s30, 0x333333
	s_mul_i32 s12, s12, s30
	s_mul_hi_u32 s12, s30, s12
	s_add_i32 s30, s30, s12
	s_mul_hi_u32 s12, s10, s30
	s_mul_i32 s12, s12, s21
	s_sub_i32 s10, s10, s12
	s_sub_i32 s12, s10, s21
	s_cmp_ge_u32 s10, s21
	s_cselect_b32 s10, s12, s10
	s_sub_i32 s12, s10, s21
	s_cmp_ge_u32 s10, s21
	s_cselect_b32 s10, s12, s10
	s_lshl_b32 s12, s20, 2
	s_abs_i32 s20, s12
	s_xor_b32 s10, s10, s11
	s_sub_i32 s10, s10, s11
	s_sub_i32 s11, 0, s20
	s_abs_i32 s30, s10
	s_xor_b32 s21, s10, s12
	s_ashr_i32 s21, s21, 31
	s_mov_b32 s31, 0x8000000
	s_mul_i32 s11, s11, s31
	s_mul_hi_u32 s11, s31, s11
	s_add_i32 s31, s31, s11
	s_mul_hi_u32 s11, s30, s31
	s_mul_i32 s31, s11, s20
	s_sub_i32 s30, s30, s31
	s_add_i32 s41, s11, 1
	s_sub_i32 s31, s30, s20
	s_cmp_ge_u32 s30, s20
	s_cselect_b32 s11, s41, s11
	s_cselect_b32 s30, s31, s30
	s_add_i32 s31, s11, 1
	s_cmp_ge_u32 s30, s20
	s_cselect_b32 s11, s31, s11
	s_xor_b32 s11, s11, s21
	s_sub_i32 s11, s11, s21
	s_lshl_b32 s20, s11, 2
	s_sub_i32 s13, s13, s20
	s_min_i32 s13, s13, 4
	s_abs_i32 s21, s13
	v_cvt_f32_u32_e32 v0, s21
	s_sub_i32 s30, 0, s21
	s_mul_i32 s11, s11, s12
	s_sub_i32 s10, s10, s11
	v_rcp_iflag_f32_e32 v0, v0
	s_abs_i32 s11, s10
	s_xor_b32 s12, s10, s13
	s_ashr_i32 s12, s12, 31
	v_mul_f32_e32 v0, 0x4f7ffffe, v0
	v_cvt_u32_f32_e32 v0, v0
	s_nop 0
	v_readfirstlane_b32 s31, v0
	s_mul_i32 s30, s30, s31
	s_mul_hi_u32 s30, s31, s30
	s_add_i32 s31, s31, s30
	s_mul_hi_u32 s30, s11, s31
	s_mul_i32 s31, s30, s21
	s_sub_i32 s11, s11, s31
	s_add_i32 s41, s30, 1
	s_sub_i32 s31, s11, s21
	s_cmp_ge_u32 s11, s21
	s_cselect_b32 s30, s41, s30
	s_cselect_b32 s11, s31, s11
	s_add_i32 s31, s30, 1
	s_cmp_ge_u32 s11, s21
	s_cselect_b32 s11, s31, s30
	s_xor_b32 s11, s11, s12
	s_sub_i32 s12, s11, s12
	s_mul_i32 s11, s12, s13
	s_sub_i32 s10, s10, s11
	s_add_i32 s89, s20, s10

;     __device__ __forceinline__ bool next(int i, Unit& u) const {
;         int nM = this->nM, nN = this->nN, Z2 = this->Z2; asm volatile("" : "+s"(nM), "+s"(nN), "+s"(Z2));
;         const long L = (long)i * G + c; if (L >= nwg) return false;
;         int wgid = (int)L; { const int q = nwg / NXCD, r = nwg % NXCD, xcd = wgid % NXCD, off = wgid / NXCD; wgid = (xcd < r ? xcd * (q + 1) : r * (q + 1) + (xcd - r) * q) + off; }
;         if (rev) wgid = nwg - 1 - wgid;
;         const int per = nM * nN, z = wgid / per, rem = wgid - z * per;
;         const int nig = WGM * nN, gid = rem / nig, fm = gid * WGM, gsz = (nM - fm) < WGM ? (nM - fm) : WGM, ri = rem - gid * nig;
;         u.pm = fm + (ri % gsz); u.pn = ri / gsz; u.z1 = z / Z2; u.z2 = z - u.z1 * Z2; return true;
; template <class Epi>
; __device__ __forceinline__ void gemm_phase(PG8_LAS unsigned char* lds, PG8_LAS unsigned char* xl, const Gemm g, const Sched& S, const Epi& E, const int wid) {
;     ...
;     if (!S.next(0, cur)) return;
.LBB0_752:
	v_readlane_b32 s8, v253, 0
	v_readlane_b32 s9, v253, 1
	v_readlane_b32 s0, v252, 41
	s_waitcnt lgkmcnt(0)
	s_barrier
	s_load_dwordx2 s[30:31], s[8:9], 0xd8
	v_readlane_b32 s4, v252, 46
	v_readlane_b32 s5, v252, 47
	s_mov_b32 s8, 8
	s_mov_b32 s9, 1
	s_movk_i32 s1, 0xa0
	s_and_b64 vcc, exec, s[4:5]
	v_mbcnt_lo_u32_b32 v8, -1, 0
	v_mbcnt_hi_u32_b32 v8, -1, v8
	s_cbranch_vccnz .LBB0_754
	s_mul_i32 s9, s1, s8
	s_abs_i32 s9, s9
	s_sub_i32 s10, 0, s9
	v_readlane_b32 s4, v254, 63
	s_nop 0
	s_mov_b32 s11, 0x333333
	s_mul_i32 s10, s10, s11
	s_mul_hi_u32 s10, s11, s10
	s_add_i32 s11, s11, s10
	s_mul_hi_u32 s10, s4, s11
	s_mul_i32 s10, s10, s9
	s_sub_i32 s10, s4, s10
	s_sub_i32 s11, s10, s9
	s_cmp_ge_u32 s10, s9
	s_cselect_b32 s10, s11, s10
	s_sub_i32 s11, s10, s9
	s_cmp_ge_u32 s10, s9
	s_cselect_b32 s9, s11, s10
	s_lshl_b32 s8, s8, 2
	s_abs_i32 s10, s8
	v_readlane_b32 s4, v254, 61
	s_sub_i32 s11, 0, s10
	s_xor_b32 s9, s9, s4
	s_sub_i32 s9, s9, s4
	s_abs_i32 s13, s9
	s_xor_b32 s12, s9, s8
	s_ashr_i32 s12, s12, 31
	s_mov_b32 s20, 0x8000000
	s_mul_i32 s11, s11, s20
	s_mul_hi_u32 s11, s20, s11
	s_add_i32 s20, s20, s11
	s_mul_hi_u32 s11, s13, s20
	s_mul_i32 s20, s11, s10
	s_sub_i32 s13, s13, s20
	s_add_i32 s21, s11, 1
	s_sub_i32 s20, s13, s10
	s_cmp_ge_u32 s13, s10
	s_cselect_b32 s11, s21, s11
	s_cselect_b32 s13, s20, s13
	s_add_i32 s20, s11, 1
	s_cmp_ge_u32 s13, s10
	s_cselect_b32 s10, s20, s11
	s_xor_b32 s10, s10, s12
	s_sub_i32 s10, s10, s12
	s_lshl_b32 s11, s10, 2
	s_sub_i32 s1, s1, s11
	s_min_i32 s1, s1, 4
	s_abs_i32 s12, s1
	v_cvt_f32_u32_e32 v0, s12
	s_sub_i32 s13, 0, s12
	s_mul_i32 s10, s10, s8
	s_sub_i32 s8, s9, s10
	v_rcp_iflag_f32_e32 v0, v0
	s_abs_i32 s9, s8
	s_xor_b32 s10, s8, s1
	s_ashr_i32 s10, s10, 31
	v_mul_f32_e32 v0, 0x4f7ffffe, v0
	v_cvt_u32_f32_e32 v0, v0
	s_nop 0
	v_readfirstlane_b32 s20, v0
	s_mul_i32 s13, s13, s20
	s_mul_hi_u32 s13, s20, s13
	s_add_i32 s20, s20, s13
	s_mul_hi_u32 s13, s9, s20
	s_mul_i32 s20, s13, s12
	s_sub_i32 s9, s9, s20
	s_add_i32 s21, s13, 1
	s_sub_i32 s20, s9, s12
	s_cmp_ge_u32 s9, s12
	s_cselect_b32 s13, s21, s13
	s_cselect_b32 s9, s20, s9
	s_add_i32 s20, s13, 1
	s_cmp_ge_u32 s9, s12
	s_cselect_b32 s9, s20, s13
	s_xor_b32 s9, s9, s10
	s_sub_i32 s12, s9, s10
	s_mul_i32 s1, s12, s1
	s_sub_i32 s1, s8, s1
	s_add_i32 s20, s11, s1

;     __device__ __forceinline__ bool next(int i, Unit& u) const {
;         int nM = this->nM, nN = this->nN, Z2 = this->Z2; asm volatile("" : "+s"(nM), "+s"(nN), "+s"(Z2));
;         const long L = (long)i * G + c; if (L >= nwg) return false;
;         int wgid = (int)L; { const int q = nwg / NXCD, r = nwg % NXCD, xcd = wgid % NXCD, off = wgid / NXCD; wgid = (xcd < r ? xcd * (q + 1) : r * (q + 1) + (xcd - r) * q) + off; }
;         if (rev) wgid = nwg - 1 - wgid;
;         const int per = nM * nN, z = wgid / per, rem = wgid - z * per;
;         const int nig = WGM * nN, gid = rem / nig, fm = gid * WGM, gsz = (nM - fm) < WGM ? (nM - fm) : WGM, ri = rem - gid * nig;
;         u.pm = fm + (ri % gsz); u.pn = ri / gsz; u.z1 = z / Z2; u.z2 = z - u.z1 * Z2; return true;
; template <class Epi>
; __device__ __forceinline__ void gemm_phase(PG8_LAS unsigned char* lds, PG8_LAS unsigned char* xl, const Gemm g, const Sched& S, const Epi& E, const int wid) {
;     ...
;         const bool has_next = S.next(ui + 1, nxt);
.LBB0_760:
	s_mov_b32 s9, 8
	s_mov_b32 s10, 1
	s_movk_i32 s8, 0xa0
	s_add_i32 s69, s69, 1
	s_mul_i32 s10, s69, s68
	s_mul_hi_u32 s11, s69, s0
	s_add_i32 s11, s11, s10
	s_mul_i32 s10, s69, s0
	s_add_u32 s10, s10, s2
	s_addc_u32 s11, s11, s33
	v_cmp_gt_i64_e32 vcc, s[10:11], v[202:203]
	v_cmp_lt_i64_e64 s[48:49], s[10:11], v[200:201]
	s_cbranch_vccnz .LBB0_762
	s_ashr_i32 s11, s10, 31
	s_lshr_b32 s11, s11, 29
	s_add_i32 s11, s10, s11
	s_ashr_i32 s13, s11, 3
	s_and_b32 s11, s11, -8
	s_sub_i32 s10, s10, s11
	s_cmp_lt_i32 s10, 0
	s_movk_i32 s4, 0xa1
	s_mul_i32 s21, s8, s9
	s_cselect_b32 s11, s4, 0xa0
	s_abs_i32 s21, s21
	s_mul_i32 s10, s10, s11
	s_sub_i32 s11, 0, s21
	s_add_i32 s10, s10, s13
	s_ashr_i32 s13, s10, 31
	s_abs_i32 s10, s10
	s_mov_b32 s30, 0x333333
	s_mul_i32 s11, s11, s30
	s_mul_hi_u32 s11, s30, s11
	s_add_i32 s30, s30, s11
	s_mul_hi_u32 s11, s10, s30
	s_mul_i32 s11, s11, s21
	s_sub_i32 s10, s10, s11
	s_sub_i32 s11, s10, s21
	s_cmp_ge_u32 s10, s21
	s_cselect_b32 s10, s11, s10
	s_sub_i32 s11, s10, s21
	s_cmp_ge_u32 s10, s21
	s_cselect_b32 s10, s11, s10
	s_lshl_b32 s9, s9, 2
	s_abs_i32 s11, s9
	s_xor_b32 s10, s10, s13
	s_sub_i32 s10, s10, s13
	s_sub_i32 s13, 0, s11
	s_abs_i32 s30, s10
	s_xor_b32 s21, s10, s9
	s_ashr_i32 s21, s21, 31
	s_mov_b32 s31, 0x8000000
	s_mul_i32 s13, s13, s31
	s_mul_hi_u32 s13, s31, s13
	s_add_i32 s31, s31, s13
	s_mul_hi_u32 s13, s30, s31
	s_mul_i32 s31, s13, s11
	s_sub_i32 s30, s30, s31
	s_add_i32 s36, s13, 1
	s_sub_i32 s31, s30, s11
	s_cmp_ge_u32 s30, s11
	s_cselect_b32 s13, s36, s13
	s_cselect_b32 s30, s31, s30
	s_add_i32 s31, s13, 1
	s_cmp_ge_u32 s30, s11
	s_cselect_b32 s11, s31, s13
	s_xor_b32 s11, s11, s21
	s_sub_i32 s11, s11, s21
	s_lshl_b32 s13, s11, 2
	s_sub_i32 s8, s8, s13
	s_min_i32 s8, s8, 4
	s_abs_i32 s21, s8
	v_cvt_f32_u32_e32 v0, s21
	s_sub_i32 s30, 0, s21
	s_mul_i32 s11, s11, s9
	s_sub_i32 s9, s10, s11
	v_rcp_iflag_f32_e32 v0, v0
	s_abs_i32 s10, s9
	s_xor_b32 s11, s9, s8
	s_ashr_i32 s11, s11, 31
	v_mul_f32_e32 v0, 0x4f7ffffe, v0
	v_cvt_u32_f32_e32 v0, v0
	s_nop 0
	v_readfirstlane_b32 s31, v0
	s_mul_i32 s30, s30, s31
	s_mul_hi_u32 s30, s31, s30
	s_add_i32 s31, s31, s30
	s_mul_hi_u32 s30, s10, s31
	s_mul_i32 s31, s30, s21
	s_sub_i32 s10, s10, s31
	s_add_i32 s36, s30, 1
	s_sub_i32 s31, s10, s21
	s_cmp_ge_u32 s10, s21
	s_cselect_b32 s30, s36, s30
	s_cselect_b32 s10, s31, s10
	s_add_i32 s31, s30, 1
	s_cmp_ge_u32 s10, s21
	s_cselect_b32 s10, s31, s30
	s_xor_b32 s10, s10, s11
	s_sub_i32 s30, s10, s11
	s_mul_i32 s8, s30, s8
	s_sub_i32 s8, s9, s8
	s_add_i32 s70, s13, s8

;     __device__ __forceinline__ bool next(int i, Unit& u) const {
;         int nM = this->nM, nN = this->nN, Z2 = this->Z2; asm volatile("" : "+s"(nM), "+s"(nN), "+s"(Z2));
;         const long L = (long)i * G + c; if (L >= nwg) return false;
;         int wgid = (int)L; { const int q = nwg / NXCD, r = nwg % NXCD, xcd = wgid % NXCD, off = wgid / NXCD; wgid = (xcd < r ? xcd * (q + 1) : r * (q + 1) + (xcd - r) * q) + off; }
;         if (rev) wgid = nwg - 1 - wgid;
;         const int per = nM * nN, z = wgid / per, rem = wgid - z * per;
;         const int nig = WGM * nN, gid = rem / nig, fm = gid * WGM, gsz = (nM - fm) < WGM ? (nM - fm) : WGM, ri = rem - gid * nig;
;         u.pm = fm + (ri % gsz); u.pn = ri / gsz; u.z1 = z / Z2; u.z2 = z - u.z1 * Z2; return true;
; template <class Epi>
; __device__ __forceinline__ void gemm_phase(PG8_LAS unsigned char* lds, PG8_LAS unsigned char* xl, const Gemm g, const Sched& S, const Epi& E, const int wid) {
;     ...
;     if (!S.next(0, cur)) return;
.LBB0_844:
	v_readlane_b32 s36, v253, 0
	v_readlane_b32 s37, v253, 1
	v_readlane_b32 s0, v252, 41
	s_waitcnt lgkmcnt(0)
	s_barrier
	s_load_dwordx2 s[30:31], s[36:37], 0xd8
	v_readlane_b32 s4, v252, 54
	v_readlane_b32 s5, v252, 55
	s_mov_b32 s8, 8
	s_mov_b32 s1, 1
	s_mov_b32 s9, 4
	s_and_b64 vcc, exec, s[4:5]
	v_mbcnt_lo_u32_b32 v8, -1, 0
	v_mbcnt_hi_u32_b32 v8, -1, v8
	s_cbranch_vccnz .LBB0_846
	s_mul_i32 s10, s8, s9
	s_abs_i32 s11, s10
	s_sub_i32 s13, 0, s11
	s_ashr_i32 s12, s10, 31
	v_readlane_b32 s4, v252, 0
	s_xor_b32 s12, s4, s12
	v_readlane_b32 s4, v252, 2
	s_mov_b32 s20, 0x8000000
	s_mul_i32 s13, s13, s20
	s_mul_hi_u32 s13, s20, s13
	s_add_i32 s20, s20, s13
	s_mul_hi_u32 s13, s4, s20
	s_mul_i32 s20, s13, s11
	s_sub_i32 s20, s4, s20
	s_add_i32 s21, s13, 1
	s_sub_i32 s40, s20, s11
	s_cmp_ge_u32 s20, s11
	s_cselect_b32 s13, s21, s13
	s_cselect_b32 s20, s40, s20
	s_add_i32 s21, s13, 1
	s_cmp_ge_u32 s20, s11
	s_cselect_b32 s11, s21, s13
	s_lshl_b32 s9, s9, 2
	s_abs_i32 s13, s9
	s_xor_b32 s11, s11, s12
	s_sub_i32 s11, s11, s12
	s_sub_i32 s12, 0, s13
	s_mul_i32 s10, s11, s10
	v_readlane_b32 s4, v252, 1
	s_sub_i32 s10, s4, s10
	s_abs_i32 s21, s10
	s_xor_b32 s20, s10, s9
	s_ashr_i32 s20, s20, 31
	s_mov_b32 s40, 0x10000000
	s_mul_i32 s12, s12, s40
	s_mul_hi_u32 s12, s40, s12
	s_add_i32 s40, s40, s12
	s_mul_hi_u32 s12, s21, s40
	s_mul_i32 s40, s12, s13
	s_sub_i32 s21, s21, s40
	s_add_i32 s41, s12, 1
	s_sub_i32 s40, s21, s13
	s_cmp_ge_u32 s21, s13
	s_cselect_b32 s12, s41, s12
	s_cselect_b32 s21, s40, s21
	s_add_i32 s40, s12, 1
	s_cmp_ge_u32 s21, s13
	s_cselect_b32 s12, s40, s12
	s_xor_b32 s12, s12, s20
	s_sub_i32 s12, s12, s20
	s_lshl_b32 s13, s12, 2
	s_sub_i32 s8, s8, s13
	s_min_i32 s8, s8, 4
	s_abs_i32 s20, s8
	v_cvt_f32_u32_e32 v0, s20
	s_sub_i32 s21, 0, s20
	s_mul_i32 s12, s12, s9
	s_sub_i32 s9, s10, s12
	v_rcp_iflag_f32_e32 v0, v0
	s_abs_i32 s10, s9
	s_xor_b32 s12, s9, s8
	s_ashr_i32 s12, s12, 31
	v_mul_f32_e32 v0, 0x4f7ffffe, v0
	v_cvt_u32_f32_e32 v0, v0
	s_nop 0
	v_readfirstlane_b32 s40, v0
	s_mul_i32 s21, s21, s40
	s_mul_hi_u32 s21, s40, s21
	s_add_i32 s40, s40, s21
	s_mul_hi_u32 s21, s10, s40
	s_mul_i32 s40, s21, s20
	s_sub_i32 s10, s10, s40
	s_add_i32 s41, s21, 1
	s_sub_i32 s40, s10, s20
	s_cmp_ge_u32 s10, s20
	s_cselect_b32 s21, s41, s21
	s_cselect_b32 s10, s40, s10
	s_add_i32 s40, s21, 1
	s_cmp_ge_u32 s10, s20
	s_cselect_b32 s10, s40, s21
	s_abs_i32 s20, s1
	s_xor_b32 s10, s10, s12
	s_sub_i32 s42, s10, s12
	s_mul_i32 s8, s42, s8
	s_sub_i32 s8, s9, s8
	s_sub_i32 s21, 0, s20
	s_add_i32 s52, s13, s8
	s_xor_b32 s1, s11, s1
	s_abs_i32 s11, s11
	s_ashr_i32 s1, s1, 31
	s_mov_b32 s8, 0xffffffff
	s_mul_i32 s21, s21, s8
	s_mul_hi_u32 s9, s8, s21
	s_add_i32 s8, s8, s9
	s_mul_hi_u32 s8, s11, s8
	s_mul_i32 s9, s8, s20
	s_sub_i32 s9, s11, s9
	s_add_i32 s10, s8, 1
	s_sub_i32 s11, s9, s20
	s_cmp_ge_u32 s9, s20
	s_cselect_b32 s8, s10, s8
	s_cselect_b32 s9, s11, s9
	s_add_i32 s10, s8, 1
	s_cmp_ge_u32 s9, s20
	s_cselect_b32 s8, s10, s8
	s_xor_b32 s8, s8, s1
	s_sub_i32 s56, s8, s1

;     __device__ __forceinline__ bool next(int i, Unit& u) const {
;         int nM = this->nM, nN = this->nN, Z2 = this->Z2; asm volatile("" : "+s"(nM), "+s"(nN), "+s"(Z2));
;         const long L = (long)i * G + c; if (L >= nwg) return false;
;         int wgid = (int)L; { const int q = nwg / NXCD, r = nwg % NXCD, xcd = wgid % NXCD, off = wgid / NXCD; wgid = (xcd < r ? xcd * (q + 1) : r * (q + 1) + (xcd - r) * q) + off; }
;         if (rev) wgid = nwg - 1 - wgid;
;         const int per = nM * nN, z = wgid / per, rem = wgid - z * per;
;         const int nig = WGM * nN, gid = rem / nig, fm = gid * WGM, gsz = (nM - fm) < WGM ? (nM - fm) : WGM, ri = rem - gid * nig;
;         u.pm = fm + (ri % gsz); u.pn = ri / gsz; u.z1 = z / Z2; u.z2 = z - u.z1 * Z2; return true;
; template <class Epi>
; __device__ __forceinline__ void gemm_phase(PG8_LAS unsigned char* lds, PG8_LAS unsigned char* xl, const Gemm g, const Sched& S, const Epi& E, const int wid) {
;     ...
;         const bool has_next = S.next(ui + 1, nxt);
.LBB0_852:
	s_add_i32 s68, s68, 1
	s_mul_i32 s10, s68, s97
	s_mul_hi_u32 s11, s68, s0
	s_add_i32 s11, s11, s10
	s_mul_i32 s10, s68, s0
	s_add_u32 s10, s10, s2
	s_addc_u32 s11, s11, s33
	v_cmp_gt_i64_e32 vcc, s[10:11], v[198:199]
	s_mov_b32 s9, 8
	s_mov_b32 s8, 1
	s_mov_b32 s13, 4
	v_cmp_lt_i64_e64 s[46:47], s[10:11], v[196:197]
	s_cbranch_vccnz .LBB0_854
	s_ashr_i32 s11, s10, 31
	s_lshr_b32 s11, s11, 29
	s_add_i32 s11, s10, s11
	s_and_b32 s12, s11, -8
	s_sub_i32 s10, s10, s12
	s_ashr_i32 s11, s11, 3
	s_cmp_lt_i32 s10, 0
	s_mul_i32 s20, s9, s13
	s_cselect_b32 s12, s4, 0xffffffb0
	s_abs_i32 s21, s20
	s_mul_i32 s10, s10, s12
	s_sub_i32 s43, 0, s21
	s_sub_i32 s10, s10, s11
	s_addk_i32 s10, 0x27f
	s_abs_i32 s12, s10
	s_xor_b32 s11, s10, s20
	s_ashr_i32 s11, s11, 31
	s_mov_b32 s44, 0x8000000
	s_mul_i32 s43, s43, s44
	s_mul_hi_u32 s43, s44, s43
	s_add_i32 s44, s44, s43
	s_mul_hi_u32 s43, s12, s44
	s_mul_i32 s44, s43, s21
	s_sub_i32 s12, s12, s44
	s_add_i32 s44, s43, 1
	s_sub_i32 s45, s12, s21
	s_cmp_ge_u32 s12, s21
	s_cselect_b32 s43, s44, s43
	s_cselect_b32 s12, s45, s12
	s_add_i32 s44, s43, 1
	s_cmp_ge_u32 s12, s21
	s_cselect_b32 s12, s44, s43
	s_lshl_b32 s13, s13, 2
	s_abs_i32 s21, s13
	s_xor_b32 s12, s12, s11
	s_sub_i32 s11, s12, s11
	s_sub_i32 s43, 0, s21
	s_mul_i32 s12, s11, s20
	s_sub_i32 s10, s10, s12
	s_abs_i32 s20, s10
	s_xor_b32 s12, s10, s13
	s_ashr_i32 s12, s12, 31
	s_mov_b32 s44, 0x10000000
	s_mul_i32 s43, s43, s44
	s_mul_hi_u32 s43, s44, s43
	s_add_i32 s44, s44, s43
	s_mul_hi_u32 s43, s20, s44
	s_mul_i32 s44, s43, s21
	s_sub_i32 s20, s20, s44
	s_add_i32 s44, s43, 1
	s_sub_i32 s45, s20, s21
	s_cmp_ge_u32 s20, s21
	s_cselect_b32 s43, s44, s43
	s_cselect_b32 s20, s45, s20
	s_add_i32 s44, s43, 1
	s_cmp_ge_u32 s20, s21
	s_cselect_b32 s20, s44, s43
	s_xor_b32 s20, s20, s12
	s_sub_i32 s12, s20, s12
	s_lshl_b32 s20, s12, 2
	s_sub_i32 s9, s9, s20
	s_min_i32 s9, s9, 4
	s_abs_i32 s21, s9
	v_cvt_f32_u32_e32 v0, s21
	s_sub_i32 s43, 0, s21
	s_mul_i32 s12, s12, s13
	s_sub_i32 s10, s10, s12
	v_rcp_iflag_f32_e32 v0, v0
	s_abs_i32 s13, s10
	s_xor_b32 s12, s10, s9
	s_ashr_i32 s12, s12, 31
	v_mul_f32_e32 v0, 0x4f7ffffe, v0
	v_cvt_u32_f32_e32 v0, v0
	s_nop 0
	v_readfirstlane_b32 s44, v0
	s_mul_i32 s43, s43, s44
	s_mul_hi_u32 s43, s44, s43
	s_add_i32 s44, s44, s43
	s_mul_hi_u32 s43, s13, s44
	s_mul_i32 s44, s43, s21
	s_sub_i32 s13, s13, s44
	s_add_i32 s44, s43, 1
	s_sub_i32 s45, s13, s21
	s_cmp_ge_u32 s13, s21
	s_cselect_b32 s43, s44, s43
	s_cselect_b32 s13, s45, s13
	s_add_i32 s44, s43, 1
	s_cmp_ge_u32 s13, s21
	s_cselect_b32 s13, s44, s43
	s_abs_i32 s21, s8
	s_xor_b32 s13, s13, s12
	s_sub_i32 s12, s13, s12
	s_mul_i32 s9, s12, s9
	s_sub_i32 s9, s10, s9
	s_add_i32 s76, s20, s9
	s_xor_b32 s8, s11, s8
	s_abs_i32 s9, s11
	s_sub_i32 s10, 0, s21
	s_ashr_i32 s8, s8, 31
	s_mov_b32 s11, 0xffffffff
	s_mul_i32 s10, s10, s11
	s_mul_hi_u32 s10, s11, s10
	s_add_i32 s11, s11, s10
	s_mul_hi_u32 s10, s9, s11
	s_mul_i32 s11, s10, s21
	s_sub_i32 s9, s9, s11
	s_add_i32 s11, s10, 1
	s_sub_i32 s13, s9, s21
	s_cmp_ge_u32 s9, s21
	s_cselect_b32 s10, s11, s10
	s_cselect_b32 s9, s13, s9
	s_add_i32 s11, s10, 1
	s_cmp_ge_u32 s9, s21
	s_cselect_b32 s9, s11, s10
	s_xor_b32 s9, s9, s8
	s_sub_i32 s60, s9, s8

;     __device__ __forceinline__ bool next(int i, Unit& u) const {
;         int nM = this->nM, nN = this->nN, Z2 = this->Z2; asm volatile("" : "+s"(nM), "+s"(nN), "+s"(Z2));
;         const long L = (long)i * G + c; if (L >= nwg) return false;
;         int wgid = (int)L; { const int q = nwg / NXCD, r = nwg % NXCD, xcd = wgid % NXCD, off = wgid / NXCD; wgid = (xcd < r ? xcd * (q + 1) : r * (q + 1) + (xcd - r) * q) + off; }
;         if (rev) wgid = nwg - 1 - wgid;
;         const int per = nM * nN, z = wgid / per, rem = wgid - z * per;
;         const int nig = WGM * nN, gid = rem / nig, fm = gid * WGM, gsz = (nM - fm) < WGM ? (nM - fm) : WGM, ri = rem - gid * nig;
;         u.pm = fm + (ri % gsz); u.pn = ri / gsz; u.z1 = z / Z2; u.z2 = z - u.z1 * Z2; return true;
; template <class Epi>
; __device__ __forceinline__ void gemm_phase(PG8_LAS unsigned char* lds, PG8_LAS unsigned char* xl, const Gemm g, const Sched& S, const Epi& E, const int wid) {
;     ...
;     if (!S.next(0, cur)) return;
.LBB0_944:
	v_readlane_b32 s8, v253, 0
	v_readlane_b32 s9, v253, 1
	v_readlane_b32 s0, v252, 41
	s_waitcnt lgkmcnt(0)
	s_barrier
	s_load_dwordx2 s[36:37], s[8:9], 0xd8
	v_readlane_b32 s4, v252, 46
	v_readlane_b32 s5, v252, 47
	s_mov_b32 s8, 8
	s_mov_b32 s9, 8
	s_mov_b32 s1, 1
	s_and_b64 vcc, exec, s[4:5]
	v_mbcnt_lo_u32_b32 v8, -1, 0
	v_mbcnt_hi_u32_b32 v8, -1, v8
	s_cbranch_vccnz .LBB0_946
	s_mul_i32 s10, s8, s9
	s_abs_i32 s11, s10
	s_sub_i32 s13, 0, s11
	s_ashr_i32 s12, s10, 31
	v_readlane_b32 s4, v254, 61
	s_xor_b32 s12, s4, s12
	v_readlane_b32 s4, v254, 63
	s_mov_b32 s20, 0x4000000
	s_mul_i32 s13, s13, s20
	s_mul_hi_u32 s13, s20, s13
	s_add_i32 s20, s20, s13
	s_mul_hi_u32 s13, s4, s20
	s_mul_i32 s20, s13, s11
	s_sub_i32 s20, s4, s20
	s_add_i32 s21, s13, 1
	s_sub_i32 s30, s20, s11
	s_cmp_ge_u32 s20, s11
	s_cselect_b32 s13, s21, s13
	s_cselect_b32 s20, s30, s20
	s_add_i32 s21, s13, 1
	s_cmp_ge_u32 s20, s11
	s_cselect_b32 s11, s21, s13
	s_lshl_b32 s9, s9, 2
	s_abs_i32 s13, s9
	s_xor_b32 s11, s11, s12
	s_sub_i32 s11, s11, s12
	s_sub_i32 s12, 0, s13
	s_mul_i32 s10, s11, s10
	v_readlane_b32 s4, v254, 62
	s_sub_i32 s10, s4, s10
	s_abs_i32 s21, s10
	s_xor_b32 s20, s10, s9
	s_ashr_i32 s20, s20, 31
	s_mov_b32 s30, 0x8000000
	s_mul_i32 s12, s12, s30
	s_mul_hi_u32 s12, s30, s12
	s_add_i32 s30, s30, s12
	s_mul_hi_u32 s12, s21, s30
	s_mul_i32 s30, s12, s13
	s_sub_i32 s21, s21, s30
	s_add_i32 s31, s12, 1
	s_sub_i32 s30, s21, s13
	s_cmp_ge_u32 s21, s13
	s_cselect_b32 s12, s31, s12
	s_cselect_b32 s21, s30, s21
	s_add_i32 s30, s12, 1
	s_cmp_ge_u32 s21, s13
	s_cselect_b32 s12, s30, s12
	s_xor_b32 s12, s12, s20
	s_sub_i32 s12, s12, s20
	s_lshl_b32 s13, s12, 2
	s_sub_i32 s8, s8, s13
	s_min_i32 s8, s8, 4
	s_abs_i32 s20, s8
	v_cvt_f32_u32_e32 v0, s20
	s_sub_i32 s21, 0, s20
	s_mul_i32 s12, s12, s9
	s_sub_i32 s9, s10, s12
	v_rcp_iflag_f32_e32 v0, v0
	s_abs_i32 s10, s9
	s_xor_b32 s12, s9, s8
	s_ashr_i32 s12, s12, 31
	v_mul_f32_e32 v0, 0x4f7ffffe, v0
	v_cvt_u32_f32_e32 v0, v0
	s_nop 0
	v_readfirstlane_b32 s30, v0
	s_mul_i32 s21, s21, s30
	s_mul_hi_u32 s21, s30, s21
	s_add_i32 s30, s30, s21
	s_mul_hi_u32 s21, s10, s30
	s_mul_i32 s30, s21, s20
	s_sub_i32 s10, s10, s30
	s_add_i32 s31, s21, 1
	s_sub_i32 s30, s10, s20
	s_cmp_ge_u32 s10, s20
	s_cselect_b32 s21, s31, s21
	s_cselect_b32 s10, s30, s10
	s_add_i32 s30, s21, 1
	s_cmp_ge_u32 s10, s20
	s_cselect_b32 s10, s30, s21
	s_abs_i32 s21, s1
	s_xor_b32 s10, s10, s12
	s_sub_i32 s12, s10, s12
	s_mul_i32 s8, s12, s8
	s_sub_i32 s8, s9, s8
	s_sub_i32 s30, 0, s21
	s_add_i32 s20, s13, s8
	s_xor_b32 s1, s11, s1
	s_abs_i32 s11, s11
	s_ashr_i32 s1, s1, 31
	s_mov_b32 s8, 0xffffffff
	s_mul_i32 s30, s30, s8
	s_mul_hi_u32 s9, s8, s30
	s_add_i32 s8, s8, s9
	s_mul_hi_u32 s8, s11, s8
	s_mul_i32 s9, s8, s21
	s_sub_i32 s9, s11, s9
	s_add_i32 s10, s8, 1
	s_sub_i32 s11, s9, s21
	s_cmp_ge_u32 s9, s21
	s_cselect_b32 s8, s10, s8
	s_cselect_b32 s9, s11, s9
	s_add_i32 s10, s8, 1
	s_cmp_ge_u32 s9, s21
	s_cselect_b32 s8, s10, s8
	s_xor_b32 s8, s8, s1
	s_sub_i32 s30, s8, s1

;     __device__ __forceinline__ bool next(int i, Unit& u) const {
;         int nM = this->nM, nN = this->nN, Z2 = this->Z2; asm volatile("" : "+s"(nM), "+s"(nN), "+s"(Z2));
;         const long L = (long)i * G + c; if (L >= nwg) return false;
;         int wgid = (int)L; { const int q = nwg / NXCD, r = nwg % NXCD, xcd = wgid % NXCD, off = wgid / NXCD; wgid = (xcd < r ? xcd * (q + 1) : r * (q + 1) + (xcd - r) * q) + off; }
;         if (rev) wgid = nwg - 1 - wgid;
;         const int per = nM * nN, z = wgid / per, rem = wgid - z * per;
;         const int nig = WGM * nN, gid = rem / nig, fm = gid * WGM, gsz = (nM - fm) < WGM ? (nM - fm) : WGM, ri = rem - gid * nig;
;         u.pm = fm + (ri % gsz); u.pn = ri / gsz; u.z1 = z / Z2; u.z2 = z - u.z1 * Z2; return true;
; template <class Epi>
; __device__ __forceinline__ void gemm_phase(PG8_LAS unsigned char* lds, PG8_LAS unsigned char* xl, const Gemm g, const Sched& S, const Epi& E, const int wid) {
;     ...
;         const bool has_next = S.next(ui + 1, nxt);
.LBB0_952:
	s_add_i32 s90, s90, 1
	s_mul_i32 s10, s90, s89
	s_mul_hi_u32 s11, s90, s0
	s_add_i32 s11, s11, s10
	s_mul_i32 s10, s90, s0
	s_add_u32 s10, s10, s2
	s_addc_u32 s11, s11, s33
	v_cmp_gt_i64_e32 vcc, s[10:11], v[202:203]
	s_mov_b32 s9, 8
	s_mov_b32 s13, 8
	s_mov_b32 s8, 1
	v_cmp_lt_i64_e64 s[46:47], s[10:11], v[200:201]
	s_cbranch_vccnz .LBB0_954
	s_ashr_i32 s11, s10, 31
	s_lshr_b32 s11, s11, 29
	s_add_i32 s11, s10, s11
	s_ashr_i32 s21, s11, 3
	s_and_b32 s11, s11, -8
	s_sub_i32 s10, s10, s11
	s_cmp_lt_i32 s10, 0
	s_movk_i32 s4, 0xa1
	s_mul_i32 s31, s9, s13
	s_cselect_b32 s11, s4, 0xa0
	s_abs_i32 s36, s31
	s_mul_i32 s10, s10, s11
	s_sub_i32 s11, 0, s36
	s_add_i32 s10, s10, s21
	s_abs_i32 s37, s10
	s_xor_b32 s21, s10, s31
	s_ashr_i32 s21, s21, 31
	s_mov_b32 s42, 0x4000000
	s_mul_i32 s11, s11, s42
	s_mul_hi_u32 s11, s42, s11
	s_add_i32 s42, s42, s11
	s_mul_hi_u32 s11, s37, s42
	s_mul_i32 s42, s11, s36
	s_sub_i32 s37, s37, s42
	s_add_i32 s42, s11, 1
	s_sub_i32 s43, s37, s36
	s_cmp_ge_u32 s37, s36
	s_cselect_b32 s11, s42, s11
	s_cselect_b32 s37, s43, s37
	s_add_i32 s42, s11, 1
	s_cmp_ge_u32 s37, s36
	s_cselect_b32 s11, s42, s11
	s_lshl_b32 s13, s13, 2
	s_abs_i32 s36, s13
	s_xor_b32 s11, s11, s21
	s_sub_i32 s11, s11, s21
	s_sub_i32 s37, 0, s36
	s_mul_i32 s21, s11, s31
	s_sub_i32 s10, s10, s21
	s_abs_i32 s31, s10
	s_xor_b32 s21, s10, s13
	s_ashr_i32 s21, s21, 31
	s_mov_b32 s42, 0x8000000
	s_mul_i32 s37, s37, s42
	s_mul_hi_u32 s37, s42, s37
	s_add_i32 s42, s42, s37
	s_mul_hi_u32 s37, s31, s42
	s_mul_i32 s42, s37, s36
	s_sub_i32 s31, s31, s42
	s_add_i32 s42, s37, 1
	s_sub_i32 s43, s31, s36
	s_cmp_ge_u32 s31, s36
	s_cselect_b32 s37, s42, s37
	s_cselect_b32 s31, s43, s31
	s_add_i32 s42, s37, 1
	s_cmp_ge_u32 s31, s36
	s_cselect_b32 s31, s42, s37
	s_xor_b32 s31, s31, s21
	s_sub_i32 s21, s31, s21
	s_lshl_b32 s31, s21, 2
	s_sub_i32 s9, s9, s31
	s_min_i32 s9, s9, 4
	s_abs_i32 s36, s9
	v_cvt_f32_u32_e32 v0, s36
	s_sub_i32 s37, 0, s36
	s_mul_i32 s21, s21, s13
	s_sub_i32 s10, s10, s21
	v_rcp_iflag_f32_e32 v0, v0
	s_abs_i32 s21, s10
	s_xor_b32 s13, s10, s9
	s_ashr_i32 s13, s13, 31
	v_mul_f32_e32 v0, 0x4f7ffffe, v0
	v_cvt_u32_f32_e32 v0, v0
	s_nop 0
	v_readfirstlane_b32 s42, v0
	s_mul_i32 s37, s37, s42
	s_mul_hi_u32 s37, s42, s37
	s_add_i32 s42, s42, s37
	s_mul_hi_u32 s37, s21, s42
	s_mul_i32 s42, s37, s36
	s_sub_i32 s21, s21, s42
	s_add_i32 s42, s37, 1
	s_sub_i32 s43, s21, s36
	s_cmp_ge_u32 s21, s36
	s_cselect_b32 s37, s42, s37
	s_cselect_b32 s21, s43, s21
	s_add_i32 s42, s37, 1
	s_cmp_ge_u32 s21, s36
	s_cselect_b32 s21, s42, s37
	s_abs_i32 s37, s8
	s_xor_b32 s21, s21, s13
	s_sub_i32 s36, s21, s13
	s_mul_i32 s9, s36, s9
	s_sub_i32 s9, s10, s9
	s_add_i32 s42, s31, s9
	s_xor_b32 s8, s11, s8
	s_abs_i32 s9, s11
	s_sub_i32 s10, 0, s37
	s_ashr_i32 s8, s8, 31
	s_mov_b32 s11, 0xffffffff
	s_mul_i32 s10, s10, s11
	s_mul_hi_u32 s10, s11, s10
	s_add_i32 s11, s11, s10
	s_mul_hi_u32 s10, s9, s11
	s_mul_i32 s11, s10, s37
	s_sub_i32 s9, s9, s11
	s_add_i32 s11, s10, 1
	s_sub_i32 s13, s9, s37
	s_cmp_ge_u32 s9, s37
	s_cselect_b32 s10, s11, s10
	s_cselect_b32 s9, s13, s9
	s_add_i32 s11, s10, 1
	s_cmp_ge_u32 s9, s37
	s_cselect_b32 s9, s11, s10
	s_xor_b32 s9, s9, s8
	s_sub_i32 s48, s9, s8

;     __device__ __forceinline__ bool next(int i, Unit& u) const {
;         int nM = this->nM, nN = this->nN, Z2 = this->Z2; asm volatile("" : "+s"(nM), "+s"(nN), "+s"(Z2));
;         const long L = (long)i * G + c; if (L >= nwg) return false;
;         int wgid = (int)L; { const int q = nwg / NXCD, r = nwg % NXCD, xcd = wgid % NXCD, off = wgid / NXCD; wgid = (xcd < r ? xcd * (q + 1) : r * (q + 1) + (xcd - r) * q) + off; }
;         if (rev) wgid = nwg - 1 - wgid;
;         const int per = nM * nN, z = wgid / per, rem = wgid - z * per;
;         const int nig = WGM * nN, gid = rem / nig, fm = gid * WGM, gsz = (nM - fm) < WGM ? (nM - fm) : WGM, ri = rem - gid * nig;
;         u.pm = fm + (ri % gsz); u.pn = ri / gsz; u.z1 = z / Z2; u.z2 = z - u.z1 * Z2; return true;
; template <class Epi>
; __device__ __forceinline__ void gemm_phase(PG8_LAS unsigned char* lds, PG8_LAS unsigned char* xl, const Gemm g, const Sched& S, const Epi& E, const int wid) {
;     ...
;     if (!S.next(0, cur)) return;
.LBB0_1095:
	v_readlane_b32 s36, v253, 0
	v_readlane_b32 s37, v253, 1
	s_waitcnt lgkmcnt(0)
	s_barrier
	v_readlane_b32 s68, v252, 41
	s_load_dwordx4 s[48:51], s[36:37], 0xb0
	s_load_dwordx2 s[20:21], s[36:37], 0xd8
	v_readlane_b32 s4, v254, 40
	v_readlane_b32 s5, v254, 41
	s_mov_b32 s8, 1
	s_mov_b32 s1, 44
	v_cndmask_b32_e64 v0, 0, 1, s[4:5]
	s_movk_i32 s0, 0xa0
	v_cmp_ne_u32_e64 s[44:45], 1, v0
	s_andn2_b64 vcc, exec, s[4:5]
	v_mbcnt_lo_u32_b32 v12, -1, 0
	v_mbcnt_hi_u32_b32 v12, -1, v12
	s_cbranch_vccnz .LBB0_1097
	s_mul_i32 s8, s0, s1
	s_abs_i32 s8, s8
	s_sub_i32 s9, 0, s8
	v_readlane_b32 s4, v254, 55
	s_nop 0
	s_mov_b32 s10, 0x94f20
	s_mul_i32 s9, s9, s10
	s_mul_hi_u32 s9, s10, s9
	s_add_i32 s10, s10, s9
	s_mul_hi_u32 s9, s4, s10
	s_mul_i32 s9, s9, s8
	s_sub_i32 s9, s4, s9
	s_sub_i32 s10, s9, s8
	s_cmp_ge_u32 s9, s8
	s_cselect_b32 s9, s10, s9
	s_sub_i32 s10, s9, s8
	s_cmp_ge_u32 s9, s8
	s_cselect_b32 s8, s10, s9
	s_lshl_b32 s1, s1, 2
	s_abs_i32 s9, s1
	v_readlane_b32 s4, v254, 54
	s_sub_i32 s10, 0, s9
	s_xor_b32 s8, s8, s4
	s_sub_i32 s8, s8, s4
	s_abs_i32 s12, s8
	s_xor_b32 s11, s8, s1
	s_ashr_i32 s11, s11, 31
	s_mov_b32 s13, 0x1745d17
	s_mul_i32 s10, s10, s13
	s_mul_hi_u32 s10, s13, s10
	s_add_i32 s13, s13, s10
	s_mul_hi_u32 s10, s12, s13
	s_mul_i32 s13, s10, s9
	s_sub_i32 s12, s12, s13
	s_add_i32 s30, s10, 1
	s_sub_i32 s13, s12, s9
	s_cmp_ge_u32 s12, s9
	s_cselect_b32 s10, s30, s10
	s_cselect_b32 s12, s13, s12
	s_add_i32 s13, s10, 1
	s_cmp_ge_u32 s12, s9
	s_cselect_b32 s9, s13, s10
	s_xor_b32 s9, s9, s11
	s_sub_i32 s9, s9, s11
	s_lshl_b32 s10, s9, 2
	s_sub_i32 s0, s0, s10
	s_min_i32 s0, s0, 4
	s_abs_i32 s11, s0
	v_cvt_f32_u32_e32 v0, s11
	s_sub_i32 s12, 0, s11
	s_mul_i32 s9, s9, s1
	s_sub_i32 s1, s8, s9
	v_rcp_iflag_f32_e32 v0, v0
	s_abs_i32 s8, s1
	s_xor_b32 s9, s1, s0
	s_ashr_i32 s9, s9, 31
	v_mul_f32_e32 v0, 0x4f7ffffe, v0
	v_cvt_u32_f32_e32 v0, v0
	s_nop 0
	v_readfirstlane_b32 s13, v0
	s_mul_i32 s12, s12, s13
	s_mul_hi_u32 s12, s13, s12
	s_add_i32 s13, s13, s12
	s_mul_hi_u32 s12, s8, s13
	s_mul_i32 s13, s12, s11
	s_sub_i32 s8, s8, s13
	s_add_i32 s30, s12, 1
	s_sub_i32 s13, s8, s11
	s_cmp_ge_u32 s8, s11
	s_cselect_b32 s12, s30, s12
	s_cselect_b32 s8, s13, s8
	s_add_i32 s13, s12, 1
	s_cmp_ge_u32 s8, s11
	s_cselect_b32 s8, s13, s12
	s_xor_b32 s8, s8, s9
	s_sub_i32 s60, s8, s9
	s_mul_i32 s0, s60, s0
	s_sub_i32 s0, s1, s0
	s_add_i32 s12, s10, s0

;     __device__ __forceinline__ bool next(int i, Unit& u) const {
;         int nM = this->nM, nN = this->nN, Z2 = this->Z2; asm volatile("" : "+s"(nM), "+s"(nN), "+s"(Z2));
;         const long L = (long)i * G + c; if (L >= nwg) return false;
;         int wgid = (int)L; { const int q = nwg / NXCD, r = nwg % NXCD, xcd = wgid % NXCD, off = wgid / NXCD; wgid = (xcd < r ? xcd * (q + 1) : r * (q + 1) + (xcd - r) * q) + off; }
;         if (rev) wgid = nwg - 1 - wgid;
;         const int per = nM * nN, z = wgid / per, rem = wgid - z * per;
;         const int nig = WGM * nN, gid = rem / nig, fm = gid * WGM, gsz = (nM - fm) < WGM ? (nM - fm) : WGM, ri = rem - gid * nig;
;         u.pm = fm + (ri % gsz); u.pn = ri / gsz; u.z1 = z / Z2; u.z2 = z - u.z1 * Z2; return true;
; template <class Epi>
; __device__ __forceinline__ void gemm_phase(PG8_LAS unsigned char* lds, PG8_LAS unsigned char* xl, const Gemm g, const Sched& S, const Epi& E, const int wid) {
;     ...
;         const bool has_next = S.next(ui + 1, nxt);
.LBB0_1103:
	s_mov_b32 s10, 1
	s_mov_b32 s9, 44
	s_movk_i32 s8, 0xa0
	s_add_i32 s67, s67, 1
	s_mul_i32 s10, s67, s66
	s_mul_hi_u32 s11, s67, s68
	s_add_i32 s11, s11, s10
	s_mul_i32 s10, s67, s68
	s_add_u32 s10, s10, s2
	s_addc_u32 s11, s11, s33
	v_cmp_gt_i64_e32 vcc, s[10:11], v[208:209]
	v_cmp_lt_i64_e64 s[46:47], s[10:11], v[206:207]
	s_cbranch_vccnz .LBB0_1105
	s_ashr_i32 s11, s10, 31
	s_lshr_b32 s11, s11, 29
	s_add_i32 s11, s10, s11
	s_and_b32 s48, s11, -8
	s_sub_i32 s10, s10, s48
	s_ashr_i32 s11, s11, 3
	s_cmp_lt_i32 s10, 0
	s_movk_i32 s4, 0xfc8f
	s_mul_i32 s49, s8, s9
	s_cselect_b32 s48, s4, 0xfffffc90
	s_abs_i32 s49, s49
	s_mul_i32 s10, s10, s48
	s_sub_i32 s48, 0, s49
	s_sub_i32 s10, s10, s11
	s_addk_i32 s10, 0x1b7f
	s_ashr_i32 s11, s10, 31
	s_abs_i32 s10, s10
	s_mov_b32 s50, 0x94f20
	s_mul_i32 s48, s48, s50
	s_mul_hi_u32 s48, s50, s48
	s_add_i32 s50, s50, s48
	s_mul_hi_u32 s48, s10, s50
	s_mul_i32 s48, s48, s49
	s_sub_i32 s10, s10, s48
	s_sub_i32 s48, s10, s49
	s_cmp_ge_u32 s10, s49
	s_cselect_b32 s10, s48, s10
	s_sub_i32 s48, s10, s49
	s_cmp_ge_u32 s10, s49
	s_cselect_b32 s10, s48, s10
	s_lshl_b32 s9, s9, 2
	s_abs_i32 s48, s9
	s_xor_b32 s10, s10, s11
	s_sub_i32 s10, s10, s11
	s_sub_i32 s11, 0, s48
	s_abs_i32 s50, s10
	s_xor_b32 s49, s10, s9
	s_ashr_i32 s49, s49, 31
	s_mov_b32 s51, 0x1745d17
	s_mul_i32 s11, s11, s51
	s_mul_hi_u32 s11, s51, s11
	s_add_i32 s51, s51, s11
	s_mul_hi_u32 s11, s50, s51
	s_mul_i32 s51, s11, s48
	s_sub_i32 s50, s50, s51
	s_add_i32 s54, s11, 1
	s_sub_i32 s51, s50, s48
	s_cmp_ge_u32 s50, s48
	s_cselect_b32 s11, s54, s11
	s_cselect_b32 s50, s51, s50
	s_add_i32 s51, s11, 1
	s_cmp_ge_u32 s50, s48
	s_cselect_b32 s11, s51, s11
	s_xor_b32 s11, s11, s49
	s_sub_i32 s11, s11, s49
	s_lshl_b32 s49, s11, 2
	s_sub_i32 s8, s8, s49
	s_min_i32 s8, s8, 4
	s_abs_i32 s48, s8
	v_cvt_f32_u32_e32 v1, s48
	s_sub_i32 s50, 0, s48
	s_mul_i32 s11, s11, s9
	s_sub_i32 s9, s10, s11
	v_rcp_iflag_f32_e32 v1, v1
	s_abs_i32 s10, s9
	s_xor_b32 s11, s9, s8
	s_ashr_i32 s11, s11, 31
	v_mul_f32_e32 v1, 0x4f7ffffe, v1
	v_cvt_u32_f32_e32 v1, v1
	s_nop 0
	v_readfirstlane_b32 s51, v1
	s_mul_i32 s50, s50, s51
	s_mul_hi_u32 s50, s51, s50
	s_add_i32 s51, s51, s50
	s_mul_hi_u32 s50, s10, s51
	s_mul_i32 s51, s50, s48
	s_sub_i32 s10, s10, s51
	s_add_i32 s54, s50, 1
	s_sub_i32 s51, s10, s48
	s_cmp_ge_u32 s10, s48
	s_cselect_b32 s50, s54, s50
	s_cselect_b32 s10, s51, s10
	s_add_i32 s51, s50, 1
	s_cmp_ge_u32 s10, s48
	s_cselect_b32 s10, s51, s50
	s_xor_b32 s10, s10, s11
	s_sub_i32 s48, s10, s11
	s_mul_i32 s8, s48, s8
	s_sub_i32 s8, s9, s8
	s_add_i32 s50, s49, s8

;     __device__ __forceinline__ bool next(int i, Unit& u) const {
;         int nM = this->nM, nN = this->nN, Z2 = this->Z2; asm volatile("" : "+s"(nM), "+s"(nN), "+s"(Z2));
;         const long L = (long)i * G + c; if (L >= nwg) return false;
;         int wgid = (int)L; { const int q = nwg / NXCD, r = nwg % NXCD, xcd = wgid % NXCD, off = wgid / NXCD; wgid = (xcd < r ? xcd * (q + 1) : r * (q + 1) + (xcd - r) * q) + off; }
;         if (rev) wgid = nwg - 1 - wgid;
;         const int per = nM * nN, z = wgid / per, rem = wgid - z * per;
;         const int nig = WGM * nN, gid = rem / nig, fm = gid * WGM, gsz = (nM - fm) < WGM ? (nM - fm) : WGM, ri = rem - gid * nig;
;         u.pm = fm + (ri % gsz); u.pn = ri / gsz; u.z1 = z / Z2; u.z2 = z - u.z1 * Z2; return true;
; template <class Epi>
; __device__ __forceinline__ void gemm_phase(PG8_LAS unsigned char* lds, PG8_LAS unsigned char* xl, const Gemm g, const Sched& S, const Epi& E, const int wid) {
;     ...
;     if (!S.next(0, cur)) return;
.LBB0_1289:
	v_readlane_b32 s0, v253, 0
	v_readlane_b32 s1, v253, 1
	v_readlane_b32 s46, v252, 41
	s_waitcnt lgkmcnt(0)
	s_barrier
	s_load_dwordx2 s[20:21], s[0:1], 0xd8
	v_readlane_b32 s4, v252, 46
	s_mov_b32 s8, 8
	s_mov_b32 s0, 1
	s_movk_i32 s1, 0xa0
	v_readlane_b32 s5, v252, 47
	v_mbcnt_lo_u32_b32 v8, -1, 0
	v_mbcnt_hi_u32_b32 v8, -1, v8
	s_and_b64 vcc, exec, s[4:5]
	s_cbranch_vccnz .LBB0_1291
	s_mul_i32 s0, s1, s8
	s_abs_i32 s0, s0
	s_sub_i32 s4, 0, s0
	v_readlane_b32 s9, v254, 63
	s_nop 0
	s_mov_b32 s5, 0x333333
	s_mul_i32 s4, s4, s5
	s_mul_hi_u32 s4, s5, s4
	s_add_i32 s5, s5, s4
	s_mul_hi_u32 s4, s9, s5
	s_mul_i32 s4, s4, s0
	s_sub_i32 s4, s9, s4
	s_sub_i32 s5, s4, s0
	s_cmp_ge_u32 s4, s0
	s_cselect_b32 s4, s5, s4
	s_sub_i32 s5, s4, s0
	s_cmp_ge_u32 s4, s0
	s_cselect_b32 s0, s5, s4
	s_lshl_b32 s4, s8, 2
	s_abs_i32 s5, s4
	v_readlane_b32 s8, v254, 61
	s_xor_b32 s0, s0, s8
	s_sub_i32 s0, s0, s8
	s_sub_i32 s8, 0, s5
	s_abs_i32 s10, s0
	s_xor_b32 s9, s0, s4
	s_ashr_i32 s9, s9, 31
	s_mov_b32 s11, 0x8000000
	s_mul_i32 s8, s8, s11
	s_mul_hi_u32 s8, s11, s8
	s_add_i32 s11, s11, s8
	s_mul_hi_u32 s8, s10, s11
	s_mul_i32 s11, s8, s5
	s_sub_i32 s10, s10, s11
	s_add_i32 s12, s8, 1
	s_sub_i32 s11, s10, s5
	s_cmp_ge_u32 s10, s5
	s_cselect_b32 s8, s12, s8
	s_cselect_b32 s10, s11, s10
	s_add_i32 s11, s8, 1
	s_cmp_ge_u32 s10, s5
	s_cselect_b32 s5, s11, s8
	s_xor_b32 s5, s5, s9
	s_sub_i32 s5, s5, s9
	s_lshl_b32 s8, s5, 2
	s_sub_i32 s1, s1, s8
	s_min_i32 s1, s1, 4
	s_abs_i32 s9, s1
	v_cvt_f32_u32_e32 v0, s9
	s_sub_i32 s10, 0, s9
	s_mul_i32 s5, s5, s4
	s_sub_i32 s4, s0, s5
	v_rcp_iflag_f32_e32 v0, v0
	s_abs_i32 s0, s4
	s_xor_b32 s5, s4, s1
	s_ashr_i32 s5, s5, 31
	v_mul_f32_e32 v0, 0x4f7ffffe, v0
	v_cvt_u32_f32_e32 v0, v0
	s_nop 0
	v_readfirstlane_b32 s11, v0
	s_mul_i32 s10, s10, s11
	s_mul_hi_u32 s10, s11, s10
	s_add_i32 s11, s11, s10
	s_mul_hi_u32 s10, s0, s11
	s_mul_i32 s11, s10, s9
	s_sub_i32 s0, s0, s11
	s_add_i32 s12, s10, 1
	s_sub_i32 s11, s0, s9
	s_cmp_ge_u32 s0, s9
	s_cselect_b32 s10, s12, s10
	s_cselect_b32 s0, s11, s0
	s_add_i32 s11, s10, 1
	s_cmp_ge_u32 s0, s9
	s_cselect_b32 s0, s11, s10
	s_xor_b32 s0, s0, s5
	s_sub_i32 s0, s0, s5
	s_mul_i32 s1, s0, s1
	s_sub_i32 s1, s4, s1
	s_add_i32 s12, s8, s1

;     __device__ __forceinline__ bool next(int i, Unit& u) const {
;         int nM = this->nM, nN = this->nN, Z2 = this->Z2; asm volatile("" : "+s"(nM), "+s"(nN), "+s"(Z2));
;         const long L = (long)i * G + c; if (L >= nwg) return false;
;         int wgid = (int)L; { const int q = nwg / NXCD, r = nwg % NXCD, xcd = wgid % NXCD, off = wgid / NXCD; wgid = (xcd < r ? xcd * (q + 1) : r * (q + 1) + (xcd - r) * q) + off; }
;         if (rev) wgid = nwg - 1 - wgid;
;         const int per = nM * nN, z = wgid / per, rem = wgid - z * per;
;         const int nig = WGM * nN, gid = rem / nig, fm = gid * WGM, gsz = (nM - fm) < WGM ? (nM - fm) : WGM, ri = rem - gid * nig;
;         u.pm = fm + (ri % gsz); u.pn = ri / gsz; u.z1 = z / Z2; u.z2 = z - u.z1 * Z2; return true;
; template <class Epi>
; __device__ __forceinline__ void gemm_phase(PG8_LAS unsigned char* lds, PG8_LAS unsigned char* xl, const Gemm g, const Sched& S, const Epi& E, const int wid) {
;     ...
;         const bool has_next = S.next(ui + 1, nxt);
.LBB0_1297:
	s_mov_b32 s8, 8
	s_mov_b32 s4, 1
	s_movk_i32 s1, 0xa0
	s_add_i32 s67, s67, 1
	s_mul_i32 s4, s67, s66
	s_mul_hi_u32 s5, s67, s46
	s_add_i32 s5, s5, s4
	s_mul_i32 s4, s67, s46
	s_add_u32 s10, s4, s2
	s_addc_u32 s11, s5, s33
	v_cmp_gt_i64_e32 vcc, s[10:11], v[202:203]
	v_cmp_lt_i64_e64 s[44:45], s[10:11], v[200:201]
	s_cbranch_vccnz .LBB0_1299
	s_ashr_i32 s4, s10, 31
	s_lshr_b32 s4, s4, 29
	s_add_i32 s4, s10, s4
	s_ashr_i32 s5, s4, 3
	s_and_b32 s4, s4, -8
	s_sub_i32 s4, s10, s4
	s_cmp_lt_i32 s4, 0
	s_movk_i32 s9, 0xa1
	s_mul_i32 s10, s1, s8
	s_cselect_b32 s9, s9, 0xa0
	s_abs_i32 s10, s10
	s_mul_i32 s4, s4, s9
	s_sub_i32 s9, 0, s10
	s_add_i32 s4, s4, s5
	s_ashr_i32 s5, s4, 31
	s_abs_i32 s4, s4
	s_mov_b32 s11, 0x333333
	s_mul_i32 s9, s9, s11
	s_mul_hi_u32 s9, s11, s9
	s_add_i32 s11, s11, s9
	s_mul_hi_u32 s9, s4, s11
	s_mul_i32 s9, s9, s10
	s_sub_i32 s4, s4, s9
	s_sub_i32 s9, s4, s10
	s_cmp_ge_u32 s4, s10
	s_cselect_b32 s4, s9, s4
	s_sub_i32 s9, s4, s10
	s_cmp_ge_u32 s4, s10
	s_cselect_b32 s4, s9, s4
	s_lshl_b32 s8, s8, 2
	s_abs_i32 s9, s8
	s_xor_b32 s4, s4, s5
	s_sub_i32 s4, s4, s5
	s_sub_i32 s5, 0, s9
	s_abs_i32 s11, s4
	s_xor_b32 s10, s4, s8
	s_ashr_i32 s10, s10, 31
	s_mov_b32 s13, 0x8000000
	s_mul_i32 s5, s5, s13
	s_mul_hi_u32 s5, s13, s5
	s_add_i32 s13, s13, s5
	s_mul_hi_u32 s5, s11, s13
	s_mul_i32 s13, s5, s9
	s_sub_i32 s11, s11, s13
	s_add_i32 s20, s5, 1
	s_sub_i32 s13, s11, s9
	s_cmp_ge_u32 s11, s9
	s_cselect_b32 s5, s20, s5
	s_cselect_b32 s11, s13, s11
	s_add_i32 s13, s5, 1
	s_cmp_ge_u32 s11, s9
	s_cselect_b32 s5, s13, s5
	s_xor_b32 s5, s5, s10
	s_sub_i32 s5, s5, s10
	s_lshl_b32 s9, s5, 2
	s_sub_i32 s1, s1, s9
	s_min_i32 s1, s1, 4
	s_abs_i32 s10, s1
	v_cvt_f32_u32_e32 v0, s10
	s_sub_i32 s11, 0, s10
	s_mul_i32 s5, s5, s8
	s_sub_i32 s4, s4, s5
	v_rcp_iflag_f32_e32 v0, v0
	s_abs_i32 s5, s4
	s_xor_b32 s8, s4, s1
	s_ashr_i32 s8, s8, 31
	v_mul_f32_e32 v0, 0x4f7ffffe, v0
	v_cvt_u32_f32_e32 v0, v0
	s_nop 0
	v_readfirstlane_b32 s13, v0
	s_mul_i32 s11, s11, s13
	s_mul_hi_u32 s11, s13, s11
	s_add_i32 s13, s13, s11
	s_mul_hi_u32 s11, s5, s13
	s_mul_i32 s13, s11, s10
	s_sub_i32 s5, s5, s13
	s_add_i32 s20, s11, 1
	s_sub_i32 s13, s5, s10
	s_cmp_ge_u32 s5, s10
	s_cselect_b32 s11, s20, s11
	s_cselect_b32 s5, s13, s5
	s_add_i32 s13, s11, 1
	s_cmp_ge_u32 s5, s10
	s_cselect_b32 s5, s13, s11
	s_xor_b32 s5, s5, s8
	s_sub_i32 s68, s5, s8
	s_mul_i32 s1, s68, s1
	s_sub_i32 s1, s4, s1
	s_add_i32 s69, s9, s1
